# attention epilogues: flat_store_short converted to global_store_short (no lgkmcnt coupling), plus DF LDS pipelining and prep loop pipelining
# baseline (speedup 1.0000x reference)
; #define LAS __attribute__((address_space(3)))
; __device__ __forceinline__ bf16_t f2bf(float f) { unsigned u = __float_as_uint(f); u += 0x7FFFu + ((u >> 16) & 1u); return (bf16_t)(u >> 16); }
; #define ATT_SYNC() do { asm volatile("s_waitcnt vmcnt(0) lgkmcnt(0)" ::: "memory"); __builtin_amdgcn_s_barrier(); asm volatile("" ::: "memory"); } while (0)
; __device__ __forceinline__ void df_unit(LAS unsigned char* lds, const bf16_t* qkv, bf16_t* attout, const float* subg, int b_, int h_, int qb_, int wid, int) {
;     ...
;     ATT_SYNC();
;     if (jsel == 0) {
;         bf16_t* op = attout + (size_t)(b * SEQ + q0 + 4 * hi) * DM + 1024 + h * 256 + r32; const LAS float* xr = xb + (4 * hi) * 256 + r32;
; #pragma unroll
;         for (int r = 0; r < 16; ++r) { const int rowc = (r & 3) + 8 * (r >> 2); float ss = 0.f;
; #pragma unroll
;             for (int d = 0; d < 8; ++d) { o[d][r] -= xr[rowc * 256 + d * 32]; ss += o[d][r] * o[d][r]; }
;             ss += __shfl_xor(ss, 1); ss += __shfl_xor(ss, 2); ss += __shfl_xor(ss, 4); ss += __shfl_xor(ss, 8); ss += __shfl_xor(ss, 16);
;             const float rstd = (1.0f - LAMBDA_INIT) / sqrtf(ss * (1.0f / 256.0f) + SUBLN_EPS);
; #pragma unroll
;             for (int d = 0; d < 8; ++d) op[d * 32] = f2bf(o[d][r] * rstd * subg[d * 32 + r32]);
;             op += ((r & 3) == 3 ? 5 : 1) * DM; asm volatile("" : "+v"(op) :: "memory"); } }
.LBB0_299:
	s_waitcnt vmcnt(0) lgkmcnt(0)
	s_barrier
	s_andn2_b64 vcc, exec, s[10:11]
	s_cbranch_vccnz .LBB0_260
	v_lshlrev_b32_e32 v3, 12, v193
	v_lshlrev_b32_e32 v13, 2, v178
	v_add3_u32 v13, s53, v3, v13
	ds_read2_b32 v[32:33], v13 offset1:32
	v_ashrrev_i32_e32 v179, 31, v178
	ds_read2_b32 v[46:47], v13 offset0:64 offset1:96
	s_lshl_b32 s0, s33, 12
	s_add_i32 s42, s42, s0
	s_waitcnt lgkmcnt(1)
	v_sub_f32_e32 v17, v177, v32
	v_sub_f32_e32 v31, v180, v33
	ds_read2_b32 v[32:33], v13 offset0:128 offset1:160
	v_mul_f32_e32 v48, v31, v31
	s_waitcnt lgkmcnt(1)
	v_sub_f32_e32 v49, v176, v46
	v_sub_f32_e32 v60, v175, v47
	ds_read2_b32 v[46:47], v13 offset0:192 offset1:224
	s_waitcnt lgkmcnt(1)
	v_sub_f32_e32 v61, v2, v32
	v_lshl_add_u64 v[2:3], v[178:179], 2, s[58:59]
	global_load_dword v62, v[2:3], off
	global_load_dword v64, v[2:3], off offset:128
	global_load_dword v65, v[2:3], off offset:256
	global_load_dword v75, v[2:3], off offset:384
	global_load_dword v76, v[2:3], off offset:640
	global_load_dword v77, v[2:3], off offset:768
	global_load_dword v78, v[2:3], off offset:896
	v_fmac_f32_e32 v48, v17, v17
	v_fmac_f32_e32 v48, v49, v49
	v_fmac_f32_e32 v48, v60, v60
	v_fmac_f32_e32 v48, v61, v61
	v_sub_f32_e32 v63, v174, v33
	v_fmac_f32_e32 v48, v63, v63
	s_waitcnt lgkmcnt(0)
	v_sub_f32_e32 v46, v173, v46
	v_fmac_f32_e32 v48, v46, v46
	v_sub_f32_e32 v47, v172, v47
	v_fmac_f32_e32 v48, v47, v47
	ds_bpermute_b32 v32, v188, v48
	s_waitcnt lgkmcnt(0)
	v_add_f32_e32 v32, v48, v32
	global_load_dword v48, v[2:3], off offset:512
	ds_bpermute_b32 v33, v187, v32
	s_waitcnt lgkmcnt(0)
	v_add_f32_e32 v32, v32, v33
	ds_bpermute_b32 v33, v186, v32
	s_waitcnt lgkmcnt(0)
	v_add_f32_e32 v32, v32, v33
	ds_bpermute_b32 v33, v185, v32
	s_waitcnt lgkmcnt(0)
	v_add_f32_e32 v32, v32, v33
	ds_bpermute_b32 v33, v184, v32
	s_waitcnt lgkmcnt(0)
	v_add_f32_e32 v32, v32, v33
	v_fmamk_f32 v32, v32, 0x3b800000, v190
	v_mul_f32_e32 v33, 0x4f800000, v32
	v_cmp_gt_f32_e32 vcc, s56, v32
	s_nop 1
	v_cndmask_b32_e32 v79, v32, v33, vcc
	v_sqrt_f32_e32 v80, v79
	v_lshl_add_u32 v32, v193, 2, s42
	v_ashrrev_i32_e32 v33, 31, v32
	v_lshlrev_b64 v[32:33], 12, v[32:33]
	v_add_u32_e32 v81, -1, v80
	v_fma_f32 v90, -v81, v80, v79
	v_cmp_ge_f32_e64 s[0:1], 0, v90
	v_add_u32_e32 v90, 1, v80
	v_lshl_add_u64 v[32:33], s[44:45], 0, v[32:33]
	v_cndmask_b32_e64 v81, v80, v81, s[0:1]
	v_fma_f32 v80, -v90, v80, v79
	v_cmp_lt_f32_e64 s[0:1], 0, v80
	v_lshl_add_u64 v[32:33], s[26:27], 1, v[32:33]
	v_lshl_add_u64 v[32:33], v[178:179], 1, v[32:33]
	v_cndmask_b32_e64 v80, v81, v90, s[0:1]
	v_mul_f32_e32 v81, 0x37800000, v80
	v_cndmask_b32_e32 v80, v80, v81, vcc
	v_cmp_class_f32_e32 vcc, v79, v189
	s_nop 1
	v_cndmask_b32_e32 v79, v80, v79, vcc
	v_div_scale_f32 v80, s[0:1], v79, v79, s87
	v_rcp_f32_e32 v81, v80
	s_nop 0
	v_fma_f32 v90, -v80, v81, 1.0
	v_fmac_f32_e32 v81, v90, v81
	v_div_scale_f32 v90, vcc, s87, v79, s87
	v_mul_f32_e32 v91, v90, v81
	v_fma_f32 v92, -v80, v91, v90
	v_fmac_f32_e32 v91, v92, v81
	v_fma_f32 v80, -v80, v91, v90
	v_div_fmas_f32 v80, v80, v81, v91
	v_div_fixup_f32 v79, v80, v79, s87
	v_mul_f32_e32 v17, v17, v79
	s_waitcnt vmcnt(7)
	v_mul_f32_e32 v17, v62, v17
	v_bfe_u32 v62, v17, 16, 1
	v_add3_u32 v17, v17, v62, s88
	global_store_short_d16_hi v[32:33], v17, off offset:2048
	v_mul_f32_e32 v17, v31, v79
	s_waitcnt vmcnt(7)
	v_mul_f32_e32 v17, v64, v17
	v_bfe_u32 v31, v17, 16, 1
	v_add3_u32 v17, v17, v31, s88
	global_store_short_d16_hi v[32:33], v17, off offset:2112
	v_mul_f32_e32 v17, v49, v79
	s_waitcnt vmcnt(7)
	v_mul_f32_e32 v17, v65, v17
	v_bfe_u32 v31, v17, 16, 1
	v_add3_u32 v17, v17, v31, s88
	global_store_short_d16_hi v[32:33], v17, off offset:2176
	v_mul_f32_e32 v17, v60, v79
	s_waitcnt vmcnt(7)
	v_mul_f32_e32 v17, v75, v17
	v_bfe_u32 v31, v17, 16, 1
	v_add3_u32 v17, v17, v31, s88
	global_store_short_d16_hi v[32:33], v17, off offset:2240
	v_mul_f32_e32 v17, v61, v79
	s_waitcnt vmcnt(4)
	v_mul_f32_e32 v17, v48, v17
	v_bfe_u32 v31, v17, 16, 1
	v_add3_u32 v17, v17, v31, s88
	global_store_short_d16_hi v[32:33], v17, off offset:2304
	v_mul_f32_e32 v17, v63, v79
	v_mul_f32_e32 v17, v17, v76
	v_bfe_u32 v31, v17, 16, 1
	v_add3_u32 v17, v17, v31, s88
	global_store_short_d16_hi v[32:33], v17, off offset:2368
	v_mul_f32_e32 v17, v46, v79
	v_mul_f32_e32 v17, v17, v77
	v_bfe_u32 v31, v17, 16, 1
	v_add3_u32 v17, v17, v31, s88
	global_store_short_d16_hi v[32:33], v17, off offset:2432
	v_mul_f32_e32 v17, v47, v79
	v_mul_f32_e32 v17, v17, v78
	v_bfe_u32 v31, v17, 16, 1
	v_add3_u32 v17, v17, v31, s88
	global_store_short_d16_hi v[32:33], v17, off offset:2496
	v_lshl_add_u64 v[32:33], v[32:33], 0, s[12:13]
	v_add_u32_e32 v17, 0x400, v13
	ds_read2_b32 v[46:47], v17 offset1:32
	ds_read2_b32 v[48:49], v17 offset0:64 offset1:96
	global_load_dword v64, v[2:3], off
	global_load_dword v65, v[2:3], off offset:256
	global_load_dword v76, v[2:3], off offset:384
	global_load_dword v77, v[2:3], off offset:512
	global_load_dword v78, v[2:3], off offset:640
	global_load_dword v79, v[2:3], off offset:768
	s_waitcnt lgkmcnt(1)
	v_sub_f32_e32 v31, v171, v46
	v_sub_f32_e32 v60, v170, v47
	ds_read2_b32 v[46:47], v17 offset0:128 offset1:160
	v_mul_f32_e32 v61, v60, v60
	s_waitcnt lgkmcnt(1)
	v_sub_f32_e32 v62, v169, v48
	v_sub_f32_e32 v63, v168, v49
	ds_read2_b32 v[48:49], v17 offset0:192 offset1:224
	v_fmac_f32_e32 v61, v31, v31
	v_fmac_f32_e32 v61, v62, v62
	v_fmac_f32_e32 v61, v63, v63
	s_waitcnt lgkmcnt(1)
	v_sub_f32_e32 v46, v167, v46
	v_fmac_f32_e32 v61, v46, v46
	v_sub_f32_e32 v17, v166, v47
	v_fmac_f32_e32 v61, v17, v17
	s_waitcnt lgkmcnt(0)
; __device__ __forceinline__ bf16_t f2bf(float f) { unsigned u = __float_as_uint(f); u += 0x7FFFu + ((u >> 16) & 1u); return (bf16_t)(u >> 16); }
; __device__ __forceinline__ void df_unit(LAS unsigned char* lds, const bf16_t* qkv, bf16_t* attout, const float* subg, int b_, int h_, int qb_, int wid, int) {
;     ...
;         for (int r = 0; r < 16; ++r) { const int rowc = (r & 3) + 8 * (r >> 2); float ss = 0.f;
; #pragma unroll
;             for (int d = 0; d < 8; ++d) { o[d][r] -= xr[rowc * 256 + d * 32]; ss += o[d][r] * o[d][r]; }
;             ss += __shfl_xor(ss, 1); ss += __shfl_xor(ss, 2); ss += __shfl_xor(ss, 4); ss += __shfl_xor(ss, 8); ss += __shfl_xor(ss, 16);
;             const float rstd = (1.0f - LAMBDA_INIT) / sqrtf(ss * (1.0f / 256.0f) + SUBLN_EPS);
; #pragma unroll
;             for (int d = 0; d < 8; ++d) op[d * 32] = f2bf(o[d][r] * rstd * subg[d * 32 + r32]);
;             op += ((r & 3) == 3 ? 5 : 1) * DM; asm volatile("" : "+v"(op) :: "memory"); } }
	v_sub_f32_e32 v48, v165, v48
	v_fmac_f32_e32 v61, v48, v48
	v_sub_f32_e32 v49, v164, v49
	v_fmac_f32_e32 v61, v49, v49
	ds_bpermute_b32 v75, v188, v61
	global_load_dword v47, v[2:3], off offset:128
	s_waitcnt lgkmcnt(0)
	v_add_f32_e32 v61, v61, v75
	ds_bpermute_b32 v75, v187, v61
	s_waitcnt lgkmcnt(0)
	v_add_f32_e32 v61, v61, v75
	ds_bpermute_b32 v75, v186, v61
	s_waitcnt lgkmcnt(0)
	v_add_f32_e32 v61, v61, v75
	ds_bpermute_b32 v75, v185, v61
	s_waitcnt lgkmcnt(0)
	v_add_f32_e32 v61, v61, v75
	global_load_dword v75, v[2:3], off offset:896
	ds_bpermute_b32 v80, v184, v61
	s_waitcnt lgkmcnt(0)
	v_add_f32_e32 v61, v61, v80
	v_fmamk_f32 v61, v61, 0x3b800000, v190
	v_mul_f32_e32 v80, 0x4f800000, v61
	v_cmp_gt_f32_e32 vcc, s56, v61
	s_nop 1
	v_cndmask_b32_e32 v61, v61, v80, vcc
	v_sqrt_f32_e32 v80, v61
	s_nop 0
	v_add_u32_e32 v81, -1, v80
	v_fma_f32 v90, -v81, v80, v61
	v_cmp_ge_f32_e64 s[0:1], 0, v90
	v_add_u32_e32 v90, 1, v80
	s_nop 0
	v_cndmask_b32_e64 v81, v80, v81, s[0:1]
	v_fma_f32 v80, -v90, v80, v61
	v_cmp_lt_f32_e64 s[0:1], 0, v80
	s_nop 1
	v_cndmask_b32_e64 v80, v81, v90, s[0:1]
	v_mul_f32_e32 v81, 0x37800000, v80
	v_cndmask_b32_e32 v80, v80, v81, vcc
	v_cmp_class_f32_e32 vcc, v61, v189
	s_nop 1
	v_cndmask_b32_e32 v61, v80, v61, vcc
	v_div_scale_f32 v80, s[0:1], v61, v61, s87
	v_rcp_f32_e32 v81, v80
	s_nop 0
	v_fma_f32 v90, -v80, v81, 1.0
	v_fmac_f32_e32 v81, v90, v81
	v_div_scale_f32 v90, vcc, s87, v61, s87
	v_mul_f32_e32 v91, v90, v81
	v_fma_f32 v92, -v80, v91, v90
	v_fmac_f32_e32 v91, v92, v81
	v_fma_f32 v80, -v80, v91, v90
	v_div_fmas_f32 v80, v80, v81, v91
	v_div_fixup_f32 v61, v80, v61, s87
	v_mul_f32_e32 v31, v31, v61
	s_waitcnt vmcnt(7)
	v_mul_f32_e32 v31, v64, v31
	v_bfe_u32 v64, v31, 16, 1
	v_add3_u32 v31, v31, v64, s88
	global_store_short_d16_hi v[32:33], v31, off
	v_mul_f32_e32 v31, v60, v61
	v_mul_f32_e32 v17, v17, v61
	s_waitcnt vmcnt(0)
	v_mul_f32_e32 v31, v47, v31
	v_bfe_u32 v47, v31, 16, 1
	v_add3_u32 v31, v31, v47, s88
	global_store_short_d16_hi v[32:33], v31, off offset:64
	v_mul_f32_e32 v31, v62, v61
	v_mul_f32_e32 v31, v65, v31
	v_bfe_u32 v47, v31, 16, 1
	v_add3_u32 v31, v31, v47, s88
	global_store_short_d16_hi v[32:33], v31, off offset:128
	v_mul_f32_e32 v31, v63, v61
	v_mul_f32_e32 v31, v76, v31
	v_bfe_u32 v47, v31, 16, 1
	v_add3_u32 v31, v31, v47, s88
	global_store_short_d16_hi v[32:33], v31, off offset:192
	v_mul_f32_e32 v31, v46, v61
	v_mul_f32_e32 v31, v77, v31
	v_bfe_u32 v46, v31, 16, 1
	v_add3_u32 v31, v31, v46, s88
	v_mul_f32_e32 v17, v17, v78
	global_store_short_d16_hi v[32:33], v31, off offset:256
	v_bfe_u32 v31, v17, 16, 1
	v_add3_u32 v17, v17, v31, s88
	global_store_short_d16_hi v[32:33], v17, off offset:320
	v_mul_f32_e32 v17, v48, v61
	v_mul_f32_e32 v17, v17, v79
	v_bfe_u32 v31, v17, 16, 1
	v_add3_u32 v17, v17, v31, s88
	global_store_short_d16_hi v[32:33], v17, off offset:384
	v_mul_f32_e32 v17, v49, v61
	v_mul_f32_e32 v17, v17, v75
	v_bfe_u32 v31, v17, 16, 1
	v_add3_u32 v17, v17, v31, s88
	global_store_short_d16_hi v[32:33], v17, off offset:448
	v_lshl_add_u64 v[32:33], v[32:33], 0, s[20:21]
	v_add_u32_e32 v17, 0x800, v13
	ds_read2_b32 v[46:47], v17 offset1:32
	ds_read2_b32 v[48:49], v17 offset0:64 offset1:96
	global_load_dword v64, v[2:3], off
	global_load_dword v65, v[2:3], off offset:256
	global_load_dword v76, v[2:3], off offset:384
	global_load_dword v77, v[2:3], off offset:512
	global_load_dword v78, v[2:3], off offset:640
	global_load_dword v79, v[2:3], off offset:768
	s_waitcnt lgkmcnt(0)
	v_sub_f32_e32 v31, v163, v46
	v_sub_f32_e32 v60, v162, v47
	ds_read2_b32 v[46:47], v17 offset0:128 offset1:160
	v_mul_f32_e32 v61, v60, v60
	v_sub_f32_e32 v62, v161, v48
	v_sub_f32_e32 v63, v160, v49
	ds_read2_b32 v[48:49], v17 offset0:192 offset1:224
	v_fmac_f32_e32 v61, v31, v31
	v_fmac_f32_e32 v61, v62, v62
	v_fmac_f32_e32 v61, v63, v63
	s_waitcnt lgkmcnt(0)
	v_sub_f32_e32 v46, v159, v46
	v_fmac_f32_e32 v61, v46, v46
	v_sub_f32_e32 v17, v158, v47
	v_fmac_f32_e32 v61, v17, v17
	v_sub_f32_e32 v48, v157, v48
	v_fmac_f32_e32 v61, v48, v48
	v_sub_f32_e32 v49, v156, v49
	v_fmac_f32_e32 v61, v49, v49
	ds_bpermute_b32 v75, v188, v61
	global_load_dword v47, v[2:3], off offset:128
	s_waitcnt lgkmcnt(0)
	v_add_f32_e32 v61, v61, v75
	ds_bpermute_b32 v75, v187, v61
	s_waitcnt lgkmcnt(0)
	v_add_f32_e32 v61, v61, v75
	ds_bpermute_b32 v75, v186, v61
	s_waitcnt lgkmcnt(0)
	v_add_f32_e32 v61, v61, v75
	ds_bpermute_b32 v75, v185, v61
	s_waitcnt lgkmcnt(0)
	v_add_f32_e32 v61, v61, v75
	global_load_dword v75, v[2:3], off offset:896
	ds_bpermute_b32 v80, v184, v61
	s_waitcnt lgkmcnt(0)
	v_add_f32_e32 v61, v61, v80
	v_fmamk_f32 v61, v61, 0x3b800000, v190
	v_mul_f32_e32 v80, 0x4f800000, v61
	v_cmp_gt_f32_e32 vcc, s56, v61
	s_nop 1
	v_cndmask_b32_e32 v61, v61, v80, vcc
	v_sqrt_f32_e32 v80, v61
	s_nop 0
	v_add_u32_e32 v81, -1, v80
	v_fma_f32 v90, -v81, v80, v61
	v_cmp_ge_f32_e64 s[0:1], 0, v90
	v_add_u32_e32 v90, 1, v80
	s_nop 0
	v_cndmask_b32_e64 v81, v80, v81, s[0:1]
	v_fma_f32 v80, -v90, v80, v61
	v_cmp_lt_f32_e64 s[0:1], 0, v80
	s_nop 1
	v_cndmask_b32_e64 v80, v81, v90, s[0:1]
	v_mul_f32_e32 v81, 0x37800000, v80
	v_cndmask_b32_e32 v80, v80, v81, vcc
	v_cmp_class_f32_e32 vcc, v61, v189
	s_nop 1
	v_cndmask_b32_e32 v61, v80, v61, vcc
	v_div_scale_f32 v80, s[0:1], v61, v61, s87
	v_rcp_f32_e32 v81, v80
	s_nop 0
	v_fma_f32 v90, -v80, v81, 1.0
	v_fmac_f32_e32 v81, v90, v81
	v_div_scale_f32 v90, vcc, s87, v61, s87
	v_mul_f32_e32 v91, v90, v81
	v_fma_f32 v92, -v80, v91, v90
	v_fmac_f32_e32 v91, v92, v81
	v_fma_f32 v80, -v80, v91, v90
	v_div_fmas_f32 v80, v80, v81, v91
	v_div_fixup_f32 v61, v80, v61, s87
	v_mul_f32_e32 v31, v31, v61
	s_waitcnt vmcnt(0)
; __device__ __forceinline__ bf16_t f2bf(float f) { unsigned u = __float_as_uint(f); u += 0x7FFFu + ((u >> 16) & 1u); return (bf16_t)(u >> 16); }
; __device__ __forceinline__ void df_unit(LAS unsigned char* lds, const bf16_t* qkv, bf16_t* attout, const float* subg, int b_, int h_, int qb_, int wid, int) {
;     ...
;         for (int r = 0; r < 16; ++r) { const int rowc = (r & 3) + 8 * (r >> 2); float ss = 0.f;
; #pragma unroll
;             for (int d = 0; d < 8; ++d) { o[d][r] -= xr[rowc * 256 + d * 32]; ss += o[d][r] * o[d][r]; }
;             ss += __shfl_xor(ss, 1); ss += __shfl_xor(ss, 2); ss += __shfl_xor(ss, 4); ss += __shfl_xor(ss, 8); ss += __shfl_xor(ss, 16);
;             const float rstd = (1.0f - LAMBDA_INIT) / sqrtf(ss * (1.0f / 256.0f) + SUBLN_EPS);
; #pragma unroll
;             for (int d = 0; d < 8; ++d) op[d * 32] = f2bf(o[d][r] * rstd * subg[d * 32 + r32]);
;             op += ((r & 3) == 3 ? 5 : 1) * DM; asm volatile("" : "+v"(op) :: "memory"); } }
	v_mul_f32_e32 v31, v64, v31
	v_bfe_u32 v64, v31, 16, 1
	v_add3_u32 v31, v31, v64, s88
	global_store_short_d16_hi v[32:33], v31, off
	v_mul_f32_e32 v31, v60, v61
	v_mul_f32_e32 v17, v17, v61
	v_mul_f32_e32 v31, v47, v31
	v_bfe_u32 v47, v31, 16, 1
	v_add3_u32 v31, v31, v47, s88
	global_store_short_d16_hi v[32:33], v31, off offset:64
	v_mul_f32_e32 v31, v62, v61
	v_mul_f32_e32 v31, v65, v31
	v_bfe_u32 v47, v31, 16, 1
	v_add3_u32 v31, v31, v47, s88
	global_store_short_d16_hi v[32:33], v31, off offset:128
	v_mul_f32_e32 v31, v63, v61
	v_mul_f32_e32 v31, v76, v31
	v_bfe_u32 v47, v31, 16, 1
	v_add3_u32 v31, v31, v47, s88
	global_store_short_d16_hi v[32:33], v31, off offset:192
	v_mul_f32_e32 v31, v46, v61
	v_mul_f32_e32 v31, v77, v31
	v_bfe_u32 v46, v31, 16, 1
	v_add3_u32 v31, v31, v46, s88
	v_mul_f32_e32 v17, v17, v78
	global_store_short_d16_hi v[32:33], v31, off offset:256
	v_bfe_u32 v31, v17, 16, 1
	v_add3_u32 v17, v17, v31, s88
	global_store_short_d16_hi v[32:33], v17, off offset:320
	v_mul_f32_e32 v17, v48, v61
	v_mul_f32_e32 v17, v17, v79
	v_bfe_u32 v31, v17, 16, 1
	v_add3_u32 v17, v17, v31, s88
	global_store_short_d16_hi v[32:33], v17, off offset:384
	v_mul_f32_e32 v17, v49, v61
	v_mul_f32_e32 v17, v17, v75
	v_bfe_u32 v31, v17, 16, 1
	v_add3_u32 v17, v17, v31, s88
	global_store_short_d16_hi v[32:33], v17, off offset:448
	v_lshl_add_u64 v[32:33], v[32:33], 0, s[20:21]
	v_add_u32_e32 v17, 0xc00, v13
	ds_read2_b32 v[46:47], v17 offset1:32
	ds_read2_b32 v[48:49], v17 offset0:64 offset1:96
	global_load_dword v64, v[2:3], off
	global_load_dword v65, v[2:3], off offset:256
	global_load_dword v76, v[2:3], off offset:384
	global_load_dword v77, v[2:3], off offset:512
	global_load_dword v78, v[2:3], off offset:640
	global_load_dword v79, v[2:3], off offset:768
	s_waitcnt lgkmcnt(0)
	v_sub_f32_e32 v31, v155, v46
	v_sub_f32_e32 v60, v154, v47
	ds_read2_b32 v[46:47], v17 offset0:128 offset1:160
	v_mul_f32_e32 v61, v60, v60
	v_sub_f32_e32 v62, v153, v48
	v_sub_f32_e32 v63, v152, v49
	ds_read2_b32 v[48:49], v17 offset0:192 offset1:224
	v_fmac_f32_e32 v61, v31, v31
	v_fmac_f32_e32 v61, v62, v62
	v_fmac_f32_e32 v61, v63, v63
	s_waitcnt lgkmcnt(0)
	v_sub_f32_e32 v46, v151, v46
	v_fmac_f32_e32 v61, v46, v46
	v_sub_f32_e32 v17, v150, v47
	v_fmac_f32_e32 v61, v17, v17
	v_sub_f32_e32 v48, v149, v48
	v_fmac_f32_e32 v61, v48, v48
	v_sub_f32_e32 v49, v148, v49
	v_fmac_f32_e32 v61, v49, v49
	ds_bpermute_b32 v75, v188, v61
	global_load_dword v47, v[2:3], off offset:128
	s_waitcnt lgkmcnt(0)
	v_add_f32_e32 v61, v61, v75
	ds_bpermute_b32 v75, v187, v61
	s_waitcnt lgkmcnt(0)
	v_add_f32_e32 v61, v61, v75
	ds_bpermute_b32 v75, v186, v61
	s_waitcnt lgkmcnt(0)
	v_add_f32_e32 v61, v61, v75
	ds_bpermute_b32 v75, v185, v61
	s_waitcnt lgkmcnt(0)
	v_add_f32_e32 v61, v61, v75
	global_load_dword v75, v[2:3], off offset:896
	ds_bpermute_b32 v80, v184, v61
	s_waitcnt lgkmcnt(0)
	v_add_f32_e32 v61, v61, v80
	v_fmamk_f32 v61, v61, 0x3b800000, v190
	v_mul_f32_e32 v80, 0x4f800000, v61
	v_cmp_gt_f32_e32 vcc, s56, v61
	s_nop 1
	v_cndmask_b32_e32 v61, v61, v80, vcc
	v_sqrt_f32_e32 v80, v61
	s_nop 0
	v_add_u32_e32 v81, -1, v80
	v_fma_f32 v90, -v81, v80, v61
	v_cmp_ge_f32_e64 s[0:1], 0, v90
	v_add_u32_e32 v90, 1, v80
	s_nop 0
	v_cndmask_b32_e64 v81, v80, v81, s[0:1]
	v_fma_f32 v80, -v90, v80, v61
	v_cmp_lt_f32_e64 s[0:1], 0, v80
	s_nop 1
	v_cndmask_b32_e64 v80, v81, v90, s[0:1]
	v_mul_f32_e32 v81, 0x37800000, v80
	v_cndmask_b32_e32 v80, v80, v81, vcc
	v_cmp_class_f32_e32 vcc, v61, v189
	s_nop 1
	v_cndmask_b32_e32 v61, v80, v61, vcc
	v_div_scale_f32 v80, s[0:1], v61, v61, s87
	v_rcp_f32_e32 v81, v80
	s_nop 0
	v_fma_f32 v90, -v80, v81, 1.0
	v_fmac_f32_e32 v81, v90, v81
	v_div_scale_f32 v90, vcc, s87, v61, s87
	v_mul_f32_e32 v91, v90, v81
	v_fma_f32 v92, -v80, v91, v90
	v_fmac_f32_e32 v91, v92, v81
	v_fma_f32 v80, -v80, v91, v90
	v_div_fmas_f32 v80, v80, v81, v91
	v_div_fixup_f32 v61, v80, v61, s87
	v_mul_f32_e32 v31, v31, v61
	s_waitcnt vmcnt(0)
	v_mul_f32_e32 v31, v64, v31
	v_bfe_u32 v64, v31, 16, 1
	v_add3_u32 v31, v31, v64, s88
	global_store_short_d16_hi v[32:33], v31, off
	v_mul_f32_e32 v31, v60, v61
	v_mul_f32_e32 v17, v17, v61
	v_mul_f32_e32 v31, v47, v31
	v_bfe_u32 v47, v31, 16, 1
	v_add3_u32 v31, v31, v47, s88
	global_store_short_d16_hi v[32:33], v31, off offset:64
	v_mul_f32_e32 v31, v62, v61
	v_mul_f32_e32 v31, v65, v31
	v_bfe_u32 v47, v31, 16, 1
	v_add3_u32 v31, v31, v47, s88
	global_store_short_d16_hi v[32:33], v31, off offset:128
	v_mul_f32_e32 v31, v63, v61
	v_mul_f32_e32 v31, v76, v31
	v_bfe_u32 v47, v31, 16, 1
	v_add3_u32 v31, v31, v47, s88
	global_store_short_d16_hi v[32:33], v31, off offset:192
	v_mul_f32_e32 v31, v46, v61
	v_mul_f32_e32 v31, v77, v31
	v_bfe_u32 v46, v31, 16, 1
	v_add3_u32 v31, v31, v46, s88
	v_mul_f32_e32 v17, v17, v78
	global_store_short_d16_hi v[32:33], v31, off offset:256
	v_bfe_u32 v31, v17, 16, 1
	v_add3_u32 v17, v17, v31, s88
	global_store_short_d16_hi v[32:33], v17, off offset:320
	v_mul_f32_e32 v17, v48, v61
	v_mul_f32_e32 v17, v17, v79
	v_bfe_u32 v31, v17, 16, 1
	v_add3_u32 v17, v17, v31, s88
	global_store_short_d16_hi v[32:33], v17, off offset:384
	v_mul_f32_e32 v17, v49, v61
	v_mul_f32_e32 v17, v17, v75
	v_bfe_u32 v31, v17, 16, 1
	v_add3_u32 v17, v17, v31, s88
	global_store_short_d16_hi v[32:33], v17, off offset:448
	v_lshl_add_u64 v[32:33], v[32:33], 0, s[22:23]
	v_add_u32_e32 v17, 0x2000, v13
	ds_read2_b32 v[46:47], v17 offset1:32
	ds_read2_b32 v[48:49], v17 offset0:64 offset1:96
	global_load_dword v64, v[2:3], off
	global_load_dword v65, v[2:3], off offset:256
	global_load_dword v76, v[2:3], off offset:384
	global_load_dword v77, v[2:3], off offset:512
	global_load_dword v78, v[2:3], off offset:640
	global_load_dword v79, v[2:3], off offset:768
	s_waitcnt lgkmcnt(0)
; __device__ __forceinline__ bf16_t f2bf(float f) { unsigned u = __float_as_uint(f); u += 0x7FFFu + ((u >> 16) & 1u); return (bf16_t)(u >> 16); }
; __device__ __forceinline__ void df_unit(LAS unsigned char* lds, const bf16_t* qkv, bf16_t* attout, const float* subg, int b_, int h_, int qb_, int wid, int) {
;     ...
;         for (int r = 0; r < 16; ++r) { const int rowc = (r & 3) + 8 * (r >> 2); float ss = 0.f;
; #pragma unroll
;             for (int d = 0; d < 8; ++d) { o[d][r] -= xr[rowc * 256 + d * 32]; ss += o[d][r] * o[d][r]; }
;             ss += __shfl_xor(ss, 1); ss += __shfl_xor(ss, 2); ss += __shfl_xor(ss, 4); ss += __shfl_xor(ss, 8); ss += __shfl_xor(ss, 16);
;             const float rstd = (1.0f - LAMBDA_INIT) / sqrtf(ss * (1.0f / 256.0f) + SUBLN_EPS);
; #pragma unroll
;             for (int d = 0; d < 8; ++d) op[d * 32] = f2bf(o[d][r] * rstd * subg[d * 32 + r32]);
;             op += ((r & 3) == 3 ? 5 : 1) * DM; asm volatile("" : "+v"(op) :: "memory"); } }
	v_sub_f32_e32 v31, v147, v46
	v_sub_f32_e32 v60, v146, v47
	ds_read2_b32 v[46:47], v17 offset0:128 offset1:160
	v_mul_f32_e32 v61, v60, v60
	v_sub_f32_e32 v62, v145, v48
	v_sub_f32_e32 v63, v144, v49
	ds_read2_b32 v[48:49], v17 offset0:192 offset1:224
	v_fmac_f32_e32 v61, v31, v31
	v_fmac_f32_e32 v61, v62, v62
	v_fmac_f32_e32 v61, v63, v63
	s_waitcnt lgkmcnt(0)
	v_sub_f32_e32 v46, v143, v46
	v_fmac_f32_e32 v61, v46, v46
	v_sub_f32_e32 v17, v142, v47
	v_fmac_f32_e32 v61, v17, v17
	v_sub_f32_e32 v48, v141, v48
	v_fmac_f32_e32 v61, v48, v48
	v_sub_f32_e32 v49, v140, v49
	v_fmac_f32_e32 v61, v49, v49
	ds_bpermute_b32 v75, v188, v61
	global_load_dword v47, v[2:3], off offset:128
	s_waitcnt lgkmcnt(0)
	v_add_f32_e32 v61, v61, v75
	ds_bpermute_b32 v75, v187, v61
	s_waitcnt lgkmcnt(0)
	v_add_f32_e32 v61, v61, v75
	ds_bpermute_b32 v75, v186, v61
	s_waitcnt lgkmcnt(0)
	v_add_f32_e32 v61, v61, v75
	ds_bpermute_b32 v75, v185, v61
	s_waitcnt lgkmcnt(0)
	v_add_f32_e32 v61, v61, v75
	global_load_dword v75, v[2:3], off offset:896
	ds_bpermute_b32 v80, v184, v61
	s_waitcnt lgkmcnt(0)
	v_add_f32_e32 v61, v61, v80
	v_fmamk_f32 v61, v61, 0x3b800000, v190
	v_mul_f32_e32 v80, 0x4f800000, v61
	v_cmp_gt_f32_e32 vcc, s56, v61
	s_nop 1
	v_cndmask_b32_e32 v61, v61, v80, vcc
	v_sqrt_f32_e32 v80, v61
	s_nop 0
	v_add_u32_e32 v81, -1, v80
	v_fma_f32 v90, -v81, v80, v61
	v_cmp_ge_f32_e64 s[0:1], 0, v90
	v_add_u32_e32 v90, 1, v80
	s_nop 0
	v_cndmask_b32_e64 v81, v80, v81, s[0:1]
	v_fma_f32 v80, -v90, v80, v61
	v_cmp_lt_f32_e64 s[0:1], 0, v80
	s_nop 1
	v_cndmask_b32_e64 v80, v81, v90, s[0:1]
	v_mul_f32_e32 v81, 0x37800000, v80
	v_cndmask_b32_e32 v80, v80, v81, vcc
	v_cmp_class_f32_e32 vcc, v61, v189
	s_nop 1
	v_cndmask_b32_e32 v61, v80, v61, vcc
	v_div_scale_f32 v80, s[0:1], v61, v61, s87
	v_rcp_f32_e32 v81, v80
	s_nop 0
	v_fma_f32 v90, -v80, v81, 1.0
	v_fmac_f32_e32 v81, v90, v81
	v_div_scale_f32 v90, vcc, s87, v61, s87
	v_mul_f32_e32 v91, v90, v81
	v_fma_f32 v92, -v80, v91, v90
	v_fmac_f32_e32 v91, v92, v81
	v_fma_f32 v80, -v80, v91, v90
	v_div_fmas_f32 v80, v80, v81, v91
	v_div_fixup_f32 v61, v80, v61, s87
	v_mul_f32_e32 v31, v31, v61
	s_waitcnt vmcnt(0)
	v_mul_f32_e32 v31, v64, v31
	v_bfe_u32 v64, v31, 16, 1
	v_add3_u32 v31, v31, v64, s88
	global_store_short_d16_hi v[32:33], v31, off
	v_mul_f32_e32 v31, v60, v61
	v_mul_f32_e32 v17, v17, v61
	v_mul_f32_e32 v31, v47, v31
	v_bfe_u32 v47, v31, 16, 1
	v_add3_u32 v31, v31, v47, s88
	global_store_short_d16_hi v[32:33], v31, off offset:64
	v_mul_f32_e32 v31, v62, v61
	v_mul_f32_e32 v31, v65, v31
	v_bfe_u32 v47, v31, 16, 1
	v_add3_u32 v31, v31, v47, s88
	global_store_short_d16_hi v[32:33], v31, off offset:128
	v_mul_f32_e32 v31, v63, v61
	v_mul_f32_e32 v31, v76, v31
	v_bfe_u32 v47, v31, 16, 1
	v_add3_u32 v31, v31, v47, s88
	global_store_short_d16_hi v[32:33], v31, off offset:192
	v_mul_f32_e32 v31, v46, v61
	v_mul_f32_e32 v31, v77, v31
	v_bfe_u32 v46, v31, 16, 1
	v_add3_u32 v31, v31, v46, s88
	v_mul_f32_e32 v17, v17, v78
	global_store_short_d16_hi v[32:33], v31, off offset:256
	v_bfe_u32 v31, v17, 16, 1
	v_add3_u32 v17, v17, v31, s88
	global_store_short_d16_hi v[32:33], v17, off offset:320
	v_mul_f32_e32 v17, v48, v61
	v_mul_f32_e32 v17, v17, v79
	v_bfe_u32 v31, v17, 16, 1
	v_add3_u32 v17, v17, v31, s88
	global_store_short_d16_hi v[32:33], v17, off offset:384
	v_mul_f32_e32 v17, v49, v61
	v_mul_f32_e32 v17, v17, v75
	v_bfe_u32 v31, v17, 16, 1
	v_add3_u32 v17, v17, v31, s88
	global_store_short_d16_hi v[32:33], v17, off offset:448
	v_lshl_add_u64 v[32:33], v[32:33], 0, s[20:21]
	v_add_u32_e32 v17, 0x2400, v13
	ds_read2_b32 v[46:47], v17 offset1:32
	ds_read2_b32 v[48:49], v17 offset0:64 offset1:96
	global_load_dword v64, v[2:3], off
	global_load_dword v65, v[2:3], off offset:256
	global_load_dword v76, v[2:3], off offset:384
	global_load_dword v77, v[2:3], off offset:512
	global_load_dword v78, v[2:3], off offset:640
	global_load_dword v79, v[2:3], off offset:768
	s_waitcnt lgkmcnt(0)
	v_sub_f32_e32 v31, v139, v46
	v_sub_f32_e32 v60, v138, v47
	ds_read2_b32 v[46:47], v17 offset0:128 offset1:160
	v_mul_f32_e32 v61, v60, v60
	v_sub_f32_e32 v62, v137, v48
	v_sub_f32_e32 v63, v136, v49
	ds_read2_b32 v[48:49], v17 offset0:192 offset1:224
	v_fmac_f32_e32 v61, v31, v31
	v_fmac_f32_e32 v61, v62, v62
	v_fmac_f32_e32 v61, v63, v63
	s_waitcnt lgkmcnt(0)
	v_sub_f32_e32 v46, v135, v46
	v_fmac_f32_e32 v61, v46, v46
	v_sub_f32_e32 v17, v134, v47
	v_fmac_f32_e32 v61, v17, v17
	v_sub_f32_e32 v48, v133, v48
	v_fmac_f32_e32 v61, v48, v48
	v_sub_f32_e32 v49, v132, v49
	v_fmac_f32_e32 v61, v49, v49
	ds_bpermute_b32 v75, v188, v61
	global_load_dword v47, v[2:3], off offset:128
	s_waitcnt lgkmcnt(0)
	v_add_f32_e32 v61, v61, v75
	ds_bpermute_b32 v75, v187, v61
	s_waitcnt lgkmcnt(0)
	v_add_f32_e32 v61, v61, v75
	ds_bpermute_b32 v75, v186, v61
	s_waitcnt lgkmcnt(0)
	v_add_f32_e32 v61, v61, v75
	ds_bpermute_b32 v75, v185, v61
	s_waitcnt lgkmcnt(0)
	v_add_f32_e32 v61, v61, v75
	global_load_dword v75, v[2:3], off offset:896
	ds_bpermute_b32 v80, v184, v61
	s_waitcnt lgkmcnt(0)
	v_add_f32_e32 v61, v61, v80
	v_fmamk_f32 v61, v61, 0x3b800000, v190
	v_mul_f32_e32 v80, 0x4f800000, v61
	v_cmp_gt_f32_e32 vcc, s56, v61
	s_nop 1
	v_cndmask_b32_e32 v61, v61, v80, vcc
	v_sqrt_f32_e32 v80, v61
	s_nop 0
	v_add_u32_e32 v81, -1, v80
	v_fma_f32 v90, -v81, v80, v61
	v_cmp_ge_f32_e64 s[0:1], 0, v90
	v_add_u32_e32 v90, 1, v80
	s_nop 0
	v_cndmask_b32_e64 v81, v80, v81, s[0:1]
	v_fma_f32 v80, -v90, v80, v61
	v_cmp_lt_f32_e64 s[0:1], 0, v80
	s_nop 1
	v_cndmask_b32_e64 v80, v81, v90, s[0:1]
	v_mul_f32_e32 v81, 0x37800000, v80
	v_cndmask_b32_e32 v80, v80, v81, vcc
	v_cmp_class_f32_e32 vcc, v61, v189
	s_nop 1
	v_cndmask_b32_e32 v61, v80, v61, vcc
	v_div_scale_f32 v80, s[0:1], v61, v61, s87
	v_rcp_f32_e32 v81, v80
	s_nop 0
	v_fma_f32 v90, -v80, v81, 1.0
	v_fmac_f32_e32 v81, v90, v81
	v_div_scale_f32 v90, vcc, s87, v61, s87
	v_mul_f32_e32 v91, v90, v81
	v_fma_f32 v92, -v80, v91, v90
	v_fmac_f32_e32 v91, v92, v81
	v_fma_f32 v80, -v80, v91, v90
	v_div_fmas_f32 v80, v80, v81, v91
	v_div_fixup_f32 v61, v80, v61, s87
	v_mul_f32_e32 v31, v31, v61
	s_waitcnt vmcnt(0)
; __device__ __forceinline__ bf16_t f2bf(float f) { unsigned u = __float_as_uint(f); u += 0x7FFFu + ((u >> 16) & 1u); return (bf16_t)(u >> 16); }
; __device__ __forceinline__ void df_unit(LAS unsigned char* lds, const bf16_t* qkv, bf16_t* attout, const float* subg, int b_, int h_, int qb_, int wid, int) {
;     ...
;         for (int r = 0; r < 16; ++r) { const int rowc = (r & 3) + 8 * (r >> 2); float ss = 0.f;
; #pragma unroll
;             for (int d = 0; d < 8; ++d) { o[d][r] -= xr[rowc * 256 + d * 32]; ss += o[d][r] * o[d][r]; }
;             ss += __shfl_xor(ss, 1); ss += __shfl_xor(ss, 2); ss += __shfl_xor(ss, 4); ss += __shfl_xor(ss, 8); ss += __shfl_xor(ss, 16);
;             const float rstd = (1.0f - LAMBDA_INIT) / sqrtf(ss * (1.0f / 256.0f) + SUBLN_EPS);
; #pragma unroll
;             for (int d = 0; d < 8; ++d) op[d * 32] = f2bf(o[d][r] * rstd * subg[d * 32 + r32]);
;             op += ((r & 3) == 3 ? 5 : 1) * DM; asm volatile("" : "+v"(op) :: "memory"); } }
	v_mul_f32_e32 v31, v64, v31
	v_bfe_u32 v64, v31, 16, 1
	v_add3_u32 v31, v31, v64, s88
	global_store_short_d16_hi v[32:33], v31, off
	v_mul_f32_e32 v31, v60, v61
	v_mul_f32_e32 v17, v17, v61
	v_mul_f32_e32 v31, v47, v31
	v_bfe_u32 v47, v31, 16, 1
	v_add3_u32 v31, v31, v47, s88
	global_store_short_d16_hi v[32:33], v31, off offset:64
	v_mul_f32_e32 v31, v62, v61
	v_mul_f32_e32 v31, v65, v31
	v_bfe_u32 v47, v31, 16, 1
	v_add3_u32 v31, v31, v47, s88
	global_store_short_d16_hi v[32:33], v31, off offset:128
	v_mul_f32_e32 v31, v63, v61
	v_mul_f32_e32 v31, v76, v31
	v_bfe_u32 v47, v31, 16, 1
	v_add3_u32 v31, v31, v47, s88
	global_store_short_d16_hi v[32:33], v31, off offset:192
	v_mul_f32_e32 v31, v46, v61
	v_mul_f32_e32 v31, v77, v31
	v_bfe_u32 v46, v31, 16, 1
	v_add3_u32 v31, v31, v46, s88
	v_mul_f32_e32 v17, v17, v78
	global_store_short_d16_hi v[32:33], v31, off offset:256
	v_bfe_u32 v31, v17, 16, 1
	v_add3_u32 v17, v17, v31, s88
	global_store_short_d16_hi v[32:33], v17, off offset:320
	v_mul_f32_e32 v17, v48, v61
	v_mul_f32_e32 v17, v17, v79
	v_bfe_u32 v31, v17, 16, 1
	v_add3_u32 v17, v17, v31, s88
	global_store_short_d16_hi v[32:33], v17, off offset:384
	v_mul_f32_e32 v17, v49, v61
	v_mul_f32_e32 v17, v17, v75
	v_bfe_u32 v31, v17, 16, 1
	v_add3_u32 v17, v17, v31, s88
	global_store_short_d16_hi v[32:33], v17, off offset:448
	v_lshl_add_u64 v[32:33], v[32:33], 0, s[20:21]
	v_add_u32_e32 v17, 0x2800, v13
	ds_read2_b32 v[46:47], v17 offset1:32
	ds_read2_b32 v[48:49], v17 offset0:64 offset1:96
	global_load_dword v64, v[2:3], off
	global_load_dword v65, v[2:3], off offset:256
	global_load_dword v76, v[2:3], off offset:384
	global_load_dword v77, v[2:3], off offset:512
	global_load_dword v78, v[2:3], off offset:640
	global_load_dword v79, v[2:3], off offset:768
	s_waitcnt lgkmcnt(0)
	v_sub_f32_e32 v31, v131, v46
	v_sub_f32_e32 v60, v130, v47
	ds_read2_b32 v[46:47], v17 offset0:128 offset1:160
	v_mul_f32_e32 v61, v60, v60
	v_sub_f32_e32 v62, v119, v48
	v_sub_f32_e32 v63, v118, v49
	ds_read2_b32 v[48:49], v17 offset0:192 offset1:224
	v_fmac_f32_e32 v61, v31, v31
	v_fmac_f32_e32 v61, v62, v62
	v_fmac_f32_e32 v61, v63, v63
	s_waitcnt lgkmcnt(0)
	v_sub_f32_e32 v46, v117, v46
	v_fmac_f32_e32 v61, v46, v46
	v_sub_f32_e32 v17, v116, v47
	v_fmac_f32_e32 v61, v17, v17
	v_sub_f32_e32 v48, v115, v48
	v_fmac_f32_e32 v61, v48, v48
	v_sub_f32_e32 v49, v114, v49
	v_fmac_f32_e32 v61, v49, v49
	ds_bpermute_b32 v75, v188, v61
	global_load_dword v47, v[2:3], off offset:128
	s_waitcnt lgkmcnt(0)
	v_add_f32_e32 v61, v61, v75
	ds_bpermute_b32 v75, v187, v61
	s_waitcnt lgkmcnt(0)
	v_add_f32_e32 v61, v61, v75
	ds_bpermute_b32 v75, v186, v61
	s_waitcnt lgkmcnt(0)
	v_add_f32_e32 v61, v61, v75
	ds_bpermute_b32 v75, v185, v61
	s_waitcnt lgkmcnt(0)
	v_add_f32_e32 v61, v61, v75
	global_load_dword v75, v[2:3], off offset:896
	ds_bpermute_b32 v80, v184, v61
	s_waitcnt lgkmcnt(0)
	v_add_f32_e32 v61, v61, v80
	v_fmamk_f32 v61, v61, 0x3b800000, v190
	v_mul_f32_e32 v80, 0x4f800000, v61
	v_cmp_gt_f32_e32 vcc, s56, v61
	s_nop 1
	v_cndmask_b32_e32 v61, v61, v80, vcc
	v_sqrt_f32_e32 v80, v61
	s_nop 0
	v_add_u32_e32 v81, -1, v80
	v_fma_f32 v90, -v81, v80, v61
	v_cmp_ge_f32_e64 s[0:1], 0, v90
	v_add_u32_e32 v90, 1, v80
	s_nop 0
	v_cndmask_b32_e64 v81, v80, v81, s[0:1]
	v_fma_f32 v80, -v90, v80, v61
	v_cmp_lt_f32_e64 s[0:1], 0, v80
	s_nop 1
	v_cndmask_b32_e64 v80, v81, v90, s[0:1]
	v_mul_f32_e32 v81, 0x37800000, v80
	v_cndmask_b32_e32 v80, v80, v81, vcc
	v_cmp_class_f32_e32 vcc, v61, v189
	s_nop 1
	v_cndmask_b32_e32 v61, v80, v61, vcc
	v_div_scale_f32 v80, s[0:1], v61, v61, s87
	v_rcp_f32_e32 v81, v80
	s_nop 0
	v_fma_f32 v90, -v80, v81, 1.0
	v_fmac_f32_e32 v81, v90, v81
	v_div_scale_f32 v90, vcc, s87, v61, s87
	v_mul_f32_e32 v91, v90, v81
	v_fma_f32 v92, -v80, v91, v90
	v_fmac_f32_e32 v91, v92, v81
	v_fma_f32 v80, -v80, v91, v90
	v_div_fmas_f32 v80, v80, v81, v91
	v_div_fixup_f32 v61, v80, v61, s87
	v_mul_f32_e32 v31, v31, v61
	s_waitcnt vmcnt(0)
	v_mul_f32_e32 v31, v64, v31
	v_bfe_u32 v64, v31, 16, 1
	v_add3_u32 v31, v31, v64, s88
	global_store_short_d16_hi v[32:33], v31, off
	v_mul_f32_e32 v31, v60, v61
	v_mul_f32_e32 v17, v17, v61
	v_mul_f32_e32 v31, v47, v31
	v_bfe_u32 v47, v31, 16, 1
	v_add3_u32 v31, v31, v47, s88
	global_store_short_d16_hi v[32:33], v31, off offset:64
	v_mul_f32_e32 v31, v62, v61
	v_mul_f32_e32 v31, v65, v31
	v_bfe_u32 v47, v31, 16, 1
	v_add3_u32 v31, v31, v47, s88
	global_store_short_d16_hi v[32:33], v31, off offset:128
	v_mul_f32_e32 v31, v63, v61
	v_mul_f32_e32 v31, v76, v31
	v_bfe_u32 v47, v31, 16, 1
	v_add3_u32 v31, v31, v47, s88
	global_store_short_d16_hi v[32:33], v31, off offset:192
	v_mul_f32_e32 v31, v46, v61
	v_mul_f32_e32 v31, v77, v31
	v_bfe_u32 v46, v31, 16, 1
	v_add3_u32 v31, v31, v46, s88
	v_mul_f32_e32 v17, v17, v78
	global_store_short_d16_hi v[32:33], v31, off offset:256
	v_bfe_u32 v31, v17, 16, 1
	v_add3_u32 v17, v17, v31, s88
	global_store_short_d16_hi v[32:33], v17, off offset:320
	v_mul_f32_e32 v17, v48, v61
	v_mul_f32_e32 v17, v17, v79
	v_bfe_u32 v31, v17, 16, 1
	v_add3_u32 v17, v17, v31, s88
	global_store_short_d16_hi v[32:33], v17, off offset:384
	v_mul_f32_e32 v17, v49, v61
	v_mul_f32_e32 v17, v17, v75
	v_bfe_u32 v31, v17, 16, 1
	v_add3_u32 v17, v17, v31, s88
	global_store_short_d16_hi v[32:33], v17, off offset:448
	v_lshl_add_u64 v[32:33], v[32:33], 0, s[20:21]
	v_add_u32_e32 v17, 0x2c00, v13
	ds_read2_b32 v[46:47], v17 offset1:32
	ds_read2_b32 v[48:49], v17 offset0:64 offset1:96
	global_load_dword v64, v[2:3], off
	global_load_dword v65, v[2:3], off offset:256
	global_load_dword v76, v[2:3], off offset:384
	global_load_dword v77, v[2:3], off offset:512
	global_load_dword v78, v[2:3], off offset:640
	global_load_dword v79, v[2:3], off offset:768
	s_waitcnt lgkmcnt(0)
; __device__ __forceinline__ bf16_t f2bf(float f) { unsigned u = __float_as_uint(f); u += 0x7FFFu + ((u >> 16) & 1u); return (bf16_t)(u >> 16); }
; __device__ __forceinline__ void df_unit(LAS unsigned char* lds, const bf16_t* qkv, bf16_t* attout, const float* subg, int b_, int h_, int qb_, int wid, int) {
;     ...
;         for (int r = 0; r < 16; ++r) { const int rowc = (r & 3) + 8 * (r >> 2); float ss = 0.f;
; #pragma unroll
;             for (int d = 0; d < 8; ++d) { o[d][r] -= xr[rowc * 256 + d * 32]; ss += o[d][r] * o[d][r]; }
;             ss += __shfl_xor(ss, 1); ss += __shfl_xor(ss, 2); ss += __shfl_xor(ss, 4); ss += __shfl_xor(ss, 8); ss += __shfl_xor(ss, 16);
;             const float rstd = (1.0f - LAMBDA_INIT) / sqrtf(ss * (1.0f / 256.0f) + SUBLN_EPS);
; #pragma unroll
;             for (int d = 0; d < 8; ++d) op[d * 32] = f2bf(o[d][r] * rstd * subg[d * 32 + r32]);
;             op += ((r & 3) == 3 ? 5 : 1) * DM; asm volatile("" : "+v"(op) :: "memory"); } }
	v_sub_f32_e32 v31, v104, v46
	v_sub_f32_e32 v60, v103, v47
	ds_read2_b32 v[46:47], v17 offset0:128 offset1:160
	v_mul_f32_e32 v61, v60, v60
	v_sub_f32_e32 v62, v102, v48
	v_sub_f32_e32 v63, v101, v49
	ds_read2_b32 v[48:49], v17 offset0:192 offset1:224
	v_fmac_f32_e32 v61, v31, v31
	v_fmac_f32_e32 v61, v62, v62
	v_fmac_f32_e32 v61, v63, v63
	s_waitcnt lgkmcnt(0)
	v_sub_f32_e32 v46, v100, v46
	v_fmac_f32_e32 v61, v46, v46
	v_sub_f32_e32 v17, v99, v47
	v_fmac_f32_e32 v61, v17, v17
	v_sub_f32_e32 v48, v98, v48
	v_fmac_f32_e32 v61, v48, v48
	v_sub_f32_e32 v49, v89, v49
	v_fmac_f32_e32 v61, v49, v49
	ds_bpermute_b32 v75, v188, v61
	global_load_dword v47, v[2:3], off offset:128
	s_waitcnt lgkmcnt(0)
	v_add_f32_e32 v61, v61, v75
	ds_bpermute_b32 v75, v187, v61
	s_waitcnt lgkmcnt(0)
	v_add_f32_e32 v61, v61, v75
	ds_bpermute_b32 v75, v186, v61
	s_waitcnt lgkmcnt(0)
	v_add_f32_e32 v61, v61, v75
	ds_bpermute_b32 v75, v185, v61
	s_waitcnt lgkmcnt(0)
	v_add_f32_e32 v61, v61, v75
	global_load_dword v75, v[2:3], off offset:896
	ds_bpermute_b32 v80, v184, v61
	s_waitcnt lgkmcnt(0)
	v_add_f32_e32 v61, v61, v80
	v_fmamk_f32 v61, v61, 0x3b800000, v190
	v_mul_f32_e32 v80, 0x4f800000, v61
	v_cmp_gt_f32_e32 vcc, s56, v61
	s_nop 1
	v_cndmask_b32_e32 v61, v61, v80, vcc
	v_sqrt_f32_e32 v80, v61
	s_nop 0
	v_add_u32_e32 v81, -1, v80
	v_fma_f32 v89, -v81, v80, v61
	v_cmp_ge_f32_e64 s[0:1], 0, v89
	v_add_u32_e32 v89, 1, v80
	s_nop 0
	v_cndmask_b32_e64 v81, v80, v81, s[0:1]
	v_fma_f32 v80, -v89, v80, v61
	v_cmp_lt_f32_e64 s[0:1], 0, v80
	s_nop 1
	v_cndmask_b32_e64 v80, v81, v89, s[0:1]
	v_mul_f32_e32 v81, 0x37800000, v80
	v_cndmask_b32_e32 v80, v80, v81, vcc
	v_cmp_class_f32_e32 vcc, v61, v189
	s_nop 1
	v_cndmask_b32_e32 v61, v80, v61, vcc
	v_div_scale_f32 v80, s[0:1], v61, v61, s87
	v_rcp_f32_e32 v81, v80
	s_nop 0
	v_fma_f32 v89, -v80, v81, 1.0
	v_fmac_f32_e32 v81, v89, v81
	v_div_scale_f32 v89, vcc, s87, v61, s87
	v_mul_f32_e32 v90, v89, v81
	v_fma_f32 v91, -v80, v90, v89
	v_fmac_f32_e32 v90, v91, v81
	v_fma_f32 v80, -v80, v90, v89
	v_div_fmas_f32 v80, v80, v81, v90
	v_div_fixup_f32 v61, v80, v61, s87
	v_mul_f32_e32 v31, v31, v61
	s_waitcnt vmcnt(0)
	v_mul_f32_e32 v31, v64, v31
	v_bfe_u32 v64, v31, 16, 1
	v_add3_u32 v31, v31, v64, s88
	global_store_short_d16_hi v[32:33], v31, off
	v_mul_f32_e32 v31, v60, v61
	v_mul_f32_e32 v17, v17, v61
	v_mul_f32_e32 v31, v47, v31
	v_bfe_u32 v47, v31, 16, 1
	v_add3_u32 v31, v31, v47, s88
	global_store_short_d16_hi v[32:33], v31, off offset:64
	v_mul_f32_e32 v31, v62, v61
	v_mul_f32_e32 v31, v65, v31
	v_bfe_u32 v47, v31, 16, 1
	v_add3_u32 v31, v31, v47, s88
	global_store_short_d16_hi v[32:33], v31, off offset:128
	v_mul_f32_e32 v31, v63, v61
	v_mul_f32_e32 v31, v76, v31
	v_bfe_u32 v47, v31, 16, 1
	v_add3_u32 v31, v31, v47, s88
	global_store_short_d16_hi v[32:33], v31, off offset:192
	v_mul_f32_e32 v31, v46, v61
	v_mul_f32_e32 v31, v77, v31
	v_bfe_u32 v46, v31, 16, 1
	v_add3_u32 v31, v31, v46, s88
	v_mul_f32_e32 v17, v17, v78
	global_store_short_d16_hi v[32:33], v31, off offset:256
	v_bfe_u32 v31, v17, 16, 1
	v_add3_u32 v17, v17, v31, s88
	global_store_short_d16_hi v[32:33], v17, off offset:320
	v_mul_f32_e32 v17, v48, v61
	v_mul_f32_e32 v17, v17, v79
	v_bfe_u32 v31, v17, 16, 1
	v_add3_u32 v17, v17, v31, s88
	global_store_short_d16_hi v[32:33], v17, off offset:384
	v_mul_f32_e32 v17, v49, v61
	v_mul_f32_e32 v17, v17, v75
	v_bfe_u32 v31, v17, 16, 1
	v_add3_u32 v17, v17, v31, s88
	global_store_short_d16_hi v[32:33], v17, off offset:448
	v_lshl_add_u64 v[32:33], v[32:33], 0, s[22:23]
	v_add_u32_e32 v17, 0x4000, v13
	ds_read2_b32 v[46:47], v17 offset1:32
	ds_read2_b32 v[48:49], v17 offset0:64 offset1:96
	global_load_dword v64, v[2:3], off
	global_load_dword v65, v[2:3], off offset:256
	global_load_dword v75, v[2:3], off offset:384
	global_load_dword v76, v[2:3], off offset:512
	global_load_dword v77, v[2:3], off offset:640
	global_load_dword v78, v[2:3], off offset:768
	s_waitcnt lgkmcnt(0)
	v_sub_f32_e32 v31, v88, v46
	v_sub_f32_e32 v60, v87, v47
	ds_read2_b32 v[46:47], v17 offset0:128 offset1:160
	v_mul_f32_e32 v61, v60, v60
	v_sub_f32_e32 v62, v86, v48
	v_sub_f32_e32 v63, v85, v49
	ds_read2_b32 v[48:49], v17 offset0:192 offset1:224
	v_fmac_f32_e32 v61, v31, v31
	v_fmac_f32_e32 v61, v62, v62
	v_fmac_f32_e32 v61, v63, v63
	s_waitcnt lgkmcnt(0)
	v_sub_f32_e32 v46, v84, v46
	v_fmac_f32_e32 v61, v46, v46
	v_sub_f32_e32 v17, v83, v47
	v_fmac_f32_e32 v61, v17, v17
	v_sub_f32_e32 v48, v82, v48
	v_fmac_f32_e32 v61, v48, v48
	v_sub_f32_e32 v49, v74, v49
	v_fmac_f32_e32 v61, v49, v49
	ds_bpermute_b32 v74, v188, v61
	global_load_dword v47, v[2:3], off offset:128
	s_waitcnt lgkmcnt(0)
	v_add_f32_e32 v61, v61, v74
	ds_bpermute_b32 v74, v187, v61
	s_waitcnt lgkmcnt(0)
	v_add_f32_e32 v61, v61, v74
	ds_bpermute_b32 v74, v186, v61
	s_waitcnt lgkmcnt(0)
	v_add_f32_e32 v61, v61, v74
	ds_bpermute_b32 v74, v185, v61
	s_waitcnt lgkmcnt(0)
	v_add_f32_e32 v61, v61, v74
	global_load_dword v74, v[2:3], off offset:896
	ds_bpermute_b32 v79, v184, v61
	s_waitcnt lgkmcnt(0)
	v_add_f32_e32 v61, v61, v79
	v_fmamk_f32 v61, v61, 0x3b800000, v190
	v_mul_f32_e32 v79, 0x4f800000, v61
	v_cmp_gt_f32_e32 vcc, s56, v61
	s_nop 1
	v_cndmask_b32_e32 v61, v61, v79, vcc
	v_sqrt_f32_e32 v79, v61
	s_nop 0
	v_add_u32_e32 v80, -1, v79
	v_fma_f32 v81, -v80, v79, v61
	v_cmp_ge_f32_e64 s[0:1], 0, v81
	v_add_u32_e32 v81, 1, v79
	s_nop 0
	v_cndmask_b32_e64 v80, v79, v80, s[0:1]
	v_fma_f32 v79, -v81, v79, v61
	v_cmp_lt_f32_e64 s[0:1], 0, v79
	s_nop 1
	v_cndmask_b32_e64 v79, v80, v81, s[0:1]
	v_mul_f32_e32 v80, 0x37800000, v79
	v_cndmask_b32_e32 v79, v79, v80, vcc
	v_cmp_class_f32_e32 vcc, v61, v189
	s_nop 1
	v_cndmask_b32_e32 v61, v79, v61, vcc
	v_div_scale_f32 v79, s[0:1], v61, v61, s87
	v_rcp_f32_e32 v80, v79
	s_nop 0
	v_fma_f32 v81, -v79, v80, 1.0
	v_fmac_f32_e32 v80, v81, v80
	v_div_scale_f32 v81, vcc, s87, v61, s87
	v_mul_f32_e32 v82, v81, v80
	v_fma_f32 v83, -v79, v82, v81
	v_fmac_f32_e32 v82, v83, v80
	v_fma_f32 v79, -v79, v82, v81
	v_div_fmas_f32 v79, v79, v80, v82
	v_div_fixup_f32 v61, v79, v61, s87
	v_mul_f32_e32 v31, v31, v61
	s_waitcnt vmcnt(0)
; __device__ __forceinline__ bf16_t f2bf(float f) { unsigned u = __float_as_uint(f); u += 0x7FFFu + ((u >> 16) & 1u); return (bf16_t)(u >> 16); }
; __device__ __forceinline__ void df_unit(LAS unsigned char* lds, const bf16_t* qkv, bf16_t* attout, const float* subg, int b_, int h_, int qb_, int wid, int) {
;     ...
;         for (int r = 0; r < 16; ++r) { const int rowc = (r & 3) + 8 * (r >> 2); float ss = 0.f;
; #pragma unroll
;             for (int d = 0; d < 8; ++d) { o[d][r] -= xr[rowc * 256 + d * 32]; ss += o[d][r] * o[d][r]; }
;             ss += __shfl_xor(ss, 1); ss += __shfl_xor(ss, 2); ss += __shfl_xor(ss, 4); ss += __shfl_xor(ss, 8); ss += __shfl_xor(ss, 16);
;             const float rstd = (1.0f - LAMBDA_INIT) / sqrtf(ss * (1.0f / 256.0f) + SUBLN_EPS);
; #pragma unroll
;             for (int d = 0; d < 8; ++d) op[d * 32] = f2bf(o[d][r] * rstd * subg[d * 32 + r32]);
;             op += ((r & 3) == 3 ? 5 : 1) * DM; asm volatile("" : "+v"(op) :: "memory"); } }
	v_mul_f32_e32 v31, v64, v31
	v_bfe_u32 v64, v31, 16, 1
	v_add3_u32 v31, v31, v64, s88
	global_store_short_d16_hi v[32:33], v31, off
	v_mul_f32_e32 v31, v60, v61
	v_mul_f32_e32 v17, v17, v61
	v_mul_f32_e32 v31, v47, v31
	v_bfe_u32 v47, v31, 16, 1
	v_add3_u32 v31, v31, v47, s88
	global_store_short_d16_hi v[32:33], v31, off offset:64
	v_mul_f32_e32 v31, v62, v61
	v_mul_f32_e32 v31, v65, v31
	v_bfe_u32 v47, v31, 16, 1
	v_add3_u32 v31, v31, v47, s88
	global_store_short_d16_hi v[32:33], v31, off offset:128
	v_mul_f32_e32 v31, v63, v61
	v_mul_f32_e32 v31, v75, v31
	v_bfe_u32 v47, v31, 16, 1
	v_add3_u32 v31, v31, v47, s88
	global_store_short_d16_hi v[32:33], v31, off offset:192
	v_mul_f32_e32 v31, v46, v61
	v_mul_f32_e32 v31, v76, v31
	v_bfe_u32 v46, v31, 16, 1
	v_add3_u32 v31, v31, v46, s88
	v_mul_f32_e32 v17, v17, v77
	global_store_short_d16_hi v[32:33], v31, off offset:256
	v_bfe_u32 v31, v17, 16, 1
	v_add3_u32 v17, v17, v31, s88
	global_store_short_d16_hi v[32:33], v17, off offset:320
	v_mul_f32_e32 v17, v48, v61
	v_mul_f32_e32 v17, v17, v78
	v_bfe_u32 v31, v17, 16, 1
	v_add3_u32 v17, v17, v31, s88
	global_store_short_d16_hi v[32:33], v17, off offset:384
	v_mul_f32_e32 v17, v49, v61
	v_mul_f32_e32 v17, v17, v74
	v_bfe_u32 v31, v17, 16, 1
	v_add3_u32 v17, v17, v31, s88
	global_store_short_d16_hi v[32:33], v17, off offset:448
	v_lshl_add_u64 v[32:33], v[32:33], 0, s[20:21]
	v_add_u32_e32 v17, 0x4400, v13
	ds_read2_b32 v[46:47], v17 offset1:32
	ds_read2_b32 v[48:49], v17 offset0:64 offset1:96
	global_load_dword v64, v[2:3], off
	global_load_dword v65, v[2:3], off offset:256
	s_waitcnt lgkmcnt(0)
	v_sub_f32_e32 v31, v73, v46
	v_sub_f32_e32 v60, v72, v47
	ds_read2_b32 v[46:47], v17 offset0:128 offset1:160
	v_mul_f32_e32 v61, v60, v60
	v_sub_f32_e32 v62, v71, v48
	v_sub_f32_e32 v63, v70, v49
	ds_read2_b32 v[48:49], v17 offset0:192 offset1:224
	v_fmac_f32_e32 v61, v31, v31
	v_fmac_f32_e32 v61, v62, v62
	v_fmac_f32_e32 v61, v63, v63
	s_waitcnt lgkmcnt(0)
	v_sub_f32_e32 v46, v69, v46
	v_fmac_f32_e32 v61, v46, v46
	v_sub_f32_e32 v17, v68, v47
	v_fmac_f32_e32 v61, v17, v17
	v_sub_f32_e32 v48, v67, v48
	v_fmac_f32_e32 v61, v48, v48
	v_sub_f32_e32 v49, v66, v49
	v_fmac_f32_e32 v61, v49, v49
	ds_bpermute_b32 v66, v188, v61
	global_load_dword v47, v[2:3], off offset:128
	global_load_dword v67, v[2:3], off offset:384
	global_load_dword v68, v[2:3], off offset:512
	global_load_dword v69, v[2:3], off offset:640
	global_load_dword v70, v[2:3], off offset:768
	s_waitcnt lgkmcnt(0)
	v_add_f32_e32 v61, v61, v66
	ds_bpermute_b32 v66, v187, v61
	s_waitcnt lgkmcnt(0)
	v_add_f32_e32 v61, v61, v66
	ds_bpermute_b32 v66, v186, v61
	s_waitcnt lgkmcnt(0)
	v_add_f32_e32 v61, v61, v66
	ds_bpermute_b32 v66, v185, v61
	s_waitcnt lgkmcnt(0)
	v_add_f32_e32 v61, v61, v66
	global_load_dword v66, v[2:3], off offset:896
	ds_bpermute_b32 v71, v184, v61
	s_waitcnt lgkmcnt(0)
	v_add_f32_e32 v61, v61, v71
	v_fmamk_f32 v61, v61, 0x3b800000, v190
	v_mul_f32_e32 v71, 0x4f800000, v61
	v_cmp_gt_f32_e32 vcc, s56, v61
	s_nop 1
	v_cndmask_b32_e32 v61, v61, v71, vcc
	v_sqrt_f32_e32 v71, v61
	s_nop 0
	v_add_u32_e32 v72, -1, v71
	v_fma_f32 v73, -v72, v71, v61
	v_cmp_ge_f32_e64 s[0:1], 0, v73
	v_add_u32_e32 v73, 1, v71
	s_nop 0
	v_cndmask_b32_e64 v72, v71, v72, s[0:1]
	v_fma_f32 v71, -v73, v71, v61
	v_cmp_lt_f32_e64 s[0:1], 0, v71
	s_nop 1
	v_cndmask_b32_e64 v71, v72, v73, s[0:1]
	v_mul_f32_e32 v72, 0x37800000, v71
	v_cndmask_b32_e32 v71, v71, v72, vcc
	v_cmp_class_f32_e32 vcc, v61, v189
	s_nop 1
	v_cndmask_b32_e32 v61, v71, v61, vcc
	v_div_scale_f32 v71, s[0:1], v61, v61, s87
	v_rcp_f32_e32 v72, v71
	s_nop 0
	v_fma_f32 v73, -v71, v72, 1.0
	v_fmac_f32_e32 v72, v73, v72
	v_div_scale_f32 v73, vcc, s87, v61, s87
	v_mul_f32_e32 v74, v73, v72
	v_fma_f32 v75, -v71, v74, v73
	v_fmac_f32_e32 v74, v75, v72
	v_fma_f32 v71, -v71, v74, v73
	v_div_fmas_f32 v71, v71, v72, v74
	v_div_fixup_f32 v61, v71, v61, s87
	v_mul_f32_e32 v31, v31, v61
	s_waitcnt vmcnt(0)
	v_mul_f32_e32 v31, v64, v31
	v_bfe_u32 v64, v31, 16, 1
	v_add3_u32 v31, v31, v64, s88
	global_store_short_d16_hi v[32:33], v31, off
	v_mul_f32_e32 v31, v60, v61
	v_mul_f32_e32 v31, v47, v31
	v_bfe_u32 v47, v31, 16, 1
	v_add3_u32 v31, v31, v47, s88
	global_store_short_d16_hi v[32:33], v31, off offset:64
	v_mul_f32_e32 v31, v62, v61
	v_mul_f32_e32 v31, v65, v31
	v_bfe_u32 v47, v31, 16, 1
	v_add3_u32 v31, v31, v47, s88
	global_store_short_d16_hi v[32:33], v31, off offset:128
	v_mul_f32_e32 v31, v63, v61
	v_mul_f32_e32 v31, v67, v31
	v_bfe_u32 v47, v31, 16, 1
	v_add3_u32 v31, v31, v47, s88
	global_store_short_d16_hi v[32:33], v31, off offset:192
	v_mul_f32_e32 v31, v46, v61
	v_mul_f32_e32 v31, v68, v31
	v_bfe_u32 v46, v31, 16, 1
	v_mul_f32_e32 v17, v17, v61
	v_add3_u32 v31, v31, v46, s88
	v_mul_f32_e32 v17, v17, v69
	global_store_short_d16_hi v[32:33], v31, off offset:256
	v_bfe_u32 v31, v17, 16, 1
	v_add3_u32 v17, v17, v31, s88
	global_store_short_d16_hi v[32:33], v17, off offset:320
	v_mul_f32_e32 v17, v48, v61
	v_mul_f32_e32 v17, v17, v70
	v_bfe_u32 v31, v17, 16, 1
	v_add3_u32 v17, v17, v31, s88
	global_store_short_d16_hi v[32:33], v17, off offset:384
	v_mul_f32_e32 v17, v49, v61
	v_mul_f32_e32 v17, v17, v66
	v_bfe_u32 v31, v17, 16, 1
	v_add3_u32 v17, v17, v31, s88
	global_store_short_d16_hi v[32:33], v17, off offset:448
	v_lshl_add_u64 v[32:33], v[32:33], 0, s[20:21]
	v_add_u32_e32 v17, 0x4800, v13
	ds_read2_b32 v[46:47], v17 offset1:32
	ds_read2_b32 v[48:49], v17 offset0:64 offset1:96
	global_load_dword v60, v[2:3], off offset:512
	global_load_dword v61, v[2:3], off offset:640
	global_load_dword v62, v[2:3], off offset:768
	s_waitcnt lgkmcnt(0)
; __device__ __forceinline__ bf16_t f2bf(float f) { unsigned u = __float_as_uint(f); u += 0x7FFFu + ((u >> 16) & 1u); return (bf16_t)(u >> 16); }
; __device__ __forceinline__ void df_unit(LAS unsigned char* lds, const bf16_t* qkv, bf16_t* attout, const float* subg, int b_, int h_, int qb_, int wid, int) {
;     ...
;         for (int r = 0; r < 16; ++r) { const int rowc = (r & 3) + 8 * (r >> 2); float ss = 0.f;
; #pragma unroll
;             for (int d = 0; d < 8; ++d) { o[d][r] -= xr[rowc * 256 + d * 32]; ss += o[d][r] * o[d][r]; }
;             ss += __shfl_xor(ss, 1); ss += __shfl_xor(ss, 2); ss += __shfl_xor(ss, 4); ss += __shfl_xor(ss, 8); ss += __shfl_xor(ss, 16);
;             const float rstd = (1.0f - LAMBDA_INIT) / sqrtf(ss * (1.0f / 256.0f) + SUBLN_EPS);
; #pragma unroll
;             for (int d = 0; d < 8; ++d) op[d * 32] = f2bf(o[d][r] * rstd * subg[d * 32 + r32]);
;             op += ((r & 3) == 3 ? 5 : 1) * DM; asm volatile("" : "+v"(op) :: "memory"); } }
	v_sub_f32_e32 v31, v59, v46
	v_sub_f32_e32 v58, v58, v47
	ds_read2_b32 v[46:47], v17 offset0:128 offset1:160
	v_mul_f32_e32 v59, v58, v58
	v_sub_f32_e32 v57, v57, v48
	v_sub_f32_e32 v56, v56, v49
	ds_read2_b32 v[48:49], v17 offset0:192 offset1:224
	v_fmac_f32_e32 v59, v31, v31
	v_fmac_f32_e32 v59, v57, v57
	v_fmac_f32_e32 v59, v56, v56
	s_waitcnt lgkmcnt(0)
	v_sub_f32_e32 v46, v55, v46
	v_fmac_f32_e32 v59, v46, v46
	v_sub_f32_e32 v17, v54, v47
	global_load_dword v55, v[2:3], off
	global_load_dword v47, v[2:3], off offset:128
	global_load_dword v54, v[2:3], off offset:384
	v_fmac_f32_e32 v59, v17, v17
	v_sub_f32_e32 v48, v53, v48
	v_fmac_f32_e32 v59, v48, v48
	v_sub_f32_e32 v49, v52, v49
	v_fmac_f32_e32 v59, v49, v49
	ds_bpermute_b32 v53, v188, v59
	global_load_dword v52, v[2:3], off offset:256
	s_waitcnt lgkmcnt(0)
	v_add_f32_e32 v53, v59, v53
	ds_bpermute_b32 v59, v187, v53
	s_waitcnt lgkmcnt(0)
	v_add_f32_e32 v53, v53, v59
	ds_bpermute_b32 v59, v186, v53
	s_waitcnt lgkmcnt(0)
	v_add_f32_e32 v53, v53, v59
	ds_bpermute_b32 v59, v185, v53
	s_waitcnt lgkmcnt(0)
	v_add_f32_e32 v53, v53, v59
	global_load_dword v59, v[2:3], off offset:896
	ds_bpermute_b32 v63, v184, v53
	s_waitcnt lgkmcnt(0)
	v_add_f32_e32 v53, v53, v63
	v_fmamk_f32 v53, v53, 0x3b800000, v190
	v_mul_f32_e32 v63, 0x4f800000, v53
	v_cmp_gt_f32_e32 vcc, s56, v53
	s_nop 1
	v_cndmask_b32_e32 v53, v53, v63, vcc
	v_sqrt_f32_e32 v63, v53
	s_nop 0
	v_add_u32_e32 v64, -1, v63
	v_fma_f32 v65, -v64, v63, v53
	v_cmp_ge_f32_e64 s[0:1], 0, v65
	v_add_u32_e32 v65, 1, v63
	s_nop 0
	v_cndmask_b32_e64 v64, v63, v64, s[0:1]
	v_fma_f32 v63, -v65, v63, v53
	v_cmp_lt_f32_e64 s[0:1], 0, v63
	s_nop 1
	v_cndmask_b32_e64 v63, v64, v65, s[0:1]
	v_mul_f32_e32 v64, 0x37800000, v63
	v_cndmask_b32_e32 v63, v63, v64, vcc
	v_cmp_class_f32_e32 vcc, v53, v189
	s_nop 1
	v_cndmask_b32_e32 v53, v63, v53, vcc
	v_div_scale_f32 v63, s[0:1], v53, v53, s87
	v_rcp_f32_e32 v64, v63
	s_nop 0
	v_fma_f32 v65, -v63, v64, 1.0
	v_fmac_f32_e32 v64, v65, v64
	v_div_scale_f32 v65, vcc, s87, v53, s87
	v_mul_f32_e32 v66, v65, v64
	v_fma_f32 v67, -v63, v66, v65
	v_fmac_f32_e32 v66, v67, v64
	v_fma_f32 v63, -v63, v66, v65
	v_div_fmas_f32 v63, v63, v64, v66
	v_div_fixup_f32 v53, v63, v53, s87
	v_mul_f32_e32 v31, v31, v53
	s_waitcnt vmcnt(0)
	v_mul_f32_e32 v31, v55, v31
	v_bfe_u32 v55, v31, 16, 1
	v_add3_u32 v31, v31, v55, s88
	global_store_short_d16_hi v[32:33], v31, off
	v_mul_f32_e32 v31, v58, v53
	v_mul_f32_e32 v31, v47, v31
	v_bfe_u32 v47, v31, 16, 1
	v_add3_u32 v31, v31, v47, s88
	global_store_short_d16_hi v[32:33], v31, off offset:64
	v_mul_f32_e32 v31, v57, v53
	v_mul_f32_e32 v31, v52, v31
	v_bfe_u32 v47, v31, 16, 1
	v_add3_u32 v31, v31, v47, s88
	global_store_short_d16_hi v[32:33], v31, off offset:128
	v_mul_f32_e32 v31, v56, v53
	v_mul_f32_e32 v31, v54, v31
	v_bfe_u32 v47, v31, 16, 1
	v_add3_u32 v31, v31, v47, s88
	global_store_short_d16_hi v[32:33], v31, off offset:192
	v_mul_f32_e32 v31, v46, v53
	v_mul_f32_e32 v31, v60, v31
	v_bfe_u32 v46, v31, 16, 1
	v_mul_f32_e32 v17, v17, v53
	v_add3_u32 v31, v31, v46, s88
	v_mul_f32_e32 v17, v17, v61
	global_store_short_d16_hi v[32:33], v31, off offset:256
	v_bfe_u32 v31, v17, 16, 1
	v_add3_u32 v17, v17, v31, s88
	global_store_short_d16_hi v[32:33], v17, off offset:320
	v_mul_f32_e32 v17, v48, v53
	v_mul_f32_e32 v17, v17, v62
	v_bfe_u32 v31, v17, 16, 1
	v_add3_u32 v17, v17, v31, s88
	global_store_short_d16_hi v[32:33], v17, off offset:384
	v_mul_f32_e32 v17, v49, v53
	v_mul_f32_e32 v17, v17, v59
	v_bfe_u32 v31, v17, 16, 1
	v_add3_u32 v17, v17, v31, s88
	global_store_short_d16_hi v[32:33], v17, off offset:448
	v_lshl_add_u64 v[32:33], v[32:33], 0, s[20:21]
	v_add_u32_e32 v17, 0x4c00, v13
	ds_read2_b32 v[46:47], v17 offset1:32
	ds_read2_b32 v[48:49], v17 offset0:64 offset1:96
	global_load_dword v52, v[2:3], off offset:512
	global_load_dword v53, v[2:3], off offset:640
	global_load_dword v54, v[2:3], off offset:768
	s_waitcnt lgkmcnt(0)
	v_sub_f32_e32 v31, v51, v46
	v_sub_f32_e32 v50, v50, v47
	ds_read2_b32 v[46:47], v17 offset0:128 offset1:160
	v_mul_f32_e32 v51, v50, v50
	v_sub_f32_e32 v48, v45, v48
	v_sub_f32_e32 v49, v44, v49
	ds_read2_b32 v[44:45], v17 offset0:192 offset1:224
	v_fmac_f32_e32 v51, v31, v31
	v_fmac_f32_e32 v51, v48, v48
	v_fmac_f32_e32 v51, v49, v49
	s_waitcnt lgkmcnt(0)
	v_sub_f32_e32 v43, v43, v46
	v_fmac_f32_e32 v51, v43, v43
	v_sub_f32_e32 v17, v42, v47
	global_load_dword v46, v[2:3], off
	global_load_dword v42, v[2:3], off offset:128
	global_load_dword v47, v[2:3], off offset:384
	v_fmac_f32_e32 v51, v17, v17
	v_sub_f32_e32 v41, v41, v44
	v_fmac_f32_e32 v51, v41, v41
	v_sub_f32_e32 v40, v40, v45
	v_fmac_f32_e32 v51, v40, v40
	ds_bpermute_b32 v45, v188, v51
	global_load_dword v44, v[2:3], off offset:256
	s_waitcnt lgkmcnt(0)
	v_add_f32_e32 v45, v51, v45
	ds_bpermute_b32 v51, v187, v45
	s_waitcnt lgkmcnt(0)
	v_add_f32_e32 v45, v45, v51
	ds_bpermute_b32 v51, v186, v45
	s_waitcnt lgkmcnt(0)
	v_add_f32_e32 v45, v45, v51
	ds_bpermute_b32 v51, v185, v45
	s_waitcnt lgkmcnt(0)
	v_add_f32_e32 v45, v45, v51
	global_load_dword v51, v[2:3], off offset:896
	ds_bpermute_b32 v55, v184, v45
	s_waitcnt lgkmcnt(0)
; __device__ __forceinline__ bf16_t f2bf(float f) { unsigned u = __float_as_uint(f); u += 0x7FFFu + ((u >> 16) & 1u); return (bf16_t)(u >> 16); }
; __device__ __forceinline__ void df_unit(LAS unsigned char* lds, const bf16_t* qkv, bf16_t* attout, const float* subg, int b_, int h_, int qb_, int wid, int) {
;     ...
;         for (int r = 0; r < 16; ++r) { const int rowc = (r & 3) + 8 * (r >> 2); float ss = 0.f;
; #pragma unroll
;             for (int d = 0; d < 8; ++d) { o[d][r] -= xr[rowc * 256 + d * 32]; ss += o[d][r] * o[d][r]; }
;             ss += __shfl_xor(ss, 1); ss += __shfl_xor(ss, 2); ss += __shfl_xor(ss, 4); ss += __shfl_xor(ss, 8); ss += __shfl_xor(ss, 16);
;             const float rstd = (1.0f - LAMBDA_INIT) / sqrtf(ss * (1.0f / 256.0f) + SUBLN_EPS);
; #pragma unroll
;             for (int d = 0; d < 8; ++d) op[d * 32] = f2bf(o[d][r] * rstd * subg[d * 32 + r32]);
;             op += ((r & 3) == 3 ? 5 : 1) * DM; asm volatile("" : "+v"(op) :: "memory"); } }
	v_add_f32_e32 v45, v45, v55
	v_fmamk_f32 v45, v45, 0x3b800000, v190
	v_mul_f32_e32 v55, 0x4f800000, v45
	v_cmp_gt_f32_e32 vcc, s56, v45
	s_nop 1
	v_cndmask_b32_e32 v45, v45, v55, vcc
	v_sqrt_f32_e32 v55, v45
	s_nop 0
	v_add_u32_e32 v56, -1, v55
	v_fma_f32 v57, -v56, v55, v45
	v_cmp_ge_f32_e64 s[0:1], 0, v57
	v_add_u32_e32 v57, 1, v55
	s_nop 0
	v_cndmask_b32_e64 v56, v55, v56, s[0:1]
	v_fma_f32 v55, -v57, v55, v45
	v_cmp_lt_f32_e64 s[0:1], 0, v55
	s_nop 1
	v_cndmask_b32_e64 v55, v56, v57, s[0:1]
	v_mul_f32_e32 v56, 0x37800000, v55
	v_cndmask_b32_e32 v55, v55, v56, vcc
	v_cmp_class_f32_e32 vcc, v45, v189
	s_nop 1
	v_cndmask_b32_e32 v45, v55, v45, vcc
	v_div_scale_f32 v55, s[0:1], v45, v45, s87
	v_rcp_f32_e32 v56, v55
	s_nop 0
	v_fma_f32 v57, -v55, v56, 1.0
	v_fmac_f32_e32 v56, v57, v56
	v_div_scale_f32 v57, vcc, s87, v45, s87
	v_mul_f32_e32 v58, v57, v56
	v_fma_f32 v59, -v55, v58, v57
	v_fmac_f32_e32 v58, v59, v56
	v_fma_f32 v55, -v55, v58, v57
	v_div_fmas_f32 v55, v55, v56, v58
	v_div_fixup_f32 v45, v55, v45, s87
	v_mul_f32_e32 v31, v31, v45
	s_waitcnt vmcnt(0)
	v_mul_f32_e32 v31, v46, v31
	v_bfe_u32 v46, v31, 16, 1
	v_add3_u32 v31, v31, v46, s88
	global_store_short_d16_hi v[32:33], v31, off
	v_mul_f32_e32 v31, v50, v45
	v_mul_f32_e32 v31, v42, v31
	v_bfe_u32 v42, v31, 16, 1
	v_add3_u32 v31, v31, v42, s88
	global_store_short_d16_hi v[32:33], v31, off offset:64
	v_mul_f32_e32 v31, v48, v45
	v_mul_f32_e32 v31, v44, v31
	v_bfe_u32 v42, v31, 16, 1
	v_add3_u32 v31, v31, v42, s88
	global_store_short_d16_hi v[32:33], v31, off offset:128
	v_mul_f32_e32 v31, v49, v45
	v_mul_f32_e32 v31, v47, v31
	v_bfe_u32 v42, v31, 16, 1
	v_add3_u32 v31, v31, v42, s88
	global_store_short_d16_hi v[32:33], v31, off offset:192
	v_mul_f32_e32 v31, v43, v45
	v_mul_f32_e32 v31, v52, v31
	v_bfe_u32 v42, v31, 16, 1
	v_mul_f32_e32 v17, v17, v45
	v_add3_u32 v31, v31, v42, s88
	v_mul_f32_e32 v17, v17, v53
	global_store_short_d16_hi v[32:33], v31, off offset:256
	v_bfe_u32 v31, v17, 16, 1
	v_add3_u32 v17, v17, v31, s88
	global_store_short_d16_hi v[32:33], v17, off offset:320
	v_mul_f32_e32 v17, v41, v45
	v_mul_f32_e32 v17, v17, v54
	v_bfe_u32 v31, v17, 16, 1
	v_add3_u32 v17, v17, v31, s88
	global_store_short_d16_hi v[32:33], v17, off offset:384
	v_mul_f32_e32 v17, v40, v45
	v_mul_f32_e32 v17, v17, v51
	v_bfe_u32 v31, v17, 16, 1
	v_add3_u32 v17, v17, v31, s88
	global_store_short_d16_hi v[32:33], v17, off offset:448
	v_lshl_add_u64 v[32:33], v[32:33], 0, s[22:23]
	v_add_u32_e32 v17, 0x6000, v13
	ds_read2_b32 v[40:41], v17 offset1:32
	ds_read2_b32 v[42:43], v17 offset0:64 offset1:96
	global_load_dword v44, v[2:3], off offset:512
	global_load_dword v45, v[2:3], off offset:640
	global_load_dword v46, v[2:3], off offset:768
	s_waitcnt lgkmcnt(0)
	v_sub_f32_e32 v31, v39, v40
	v_sub_f32_e32 v40, v38, v41
	ds_read2_b32 v[38:39], v17 offset0:128 offset1:160
	v_mul_f32_e32 v41, v40, v40
	v_sub_f32_e32 v42, v37, v42
	v_sub_f32_e32 v43, v36, v43
	ds_read2_b32 v[36:37], v17 offset0:192 offset1:224
	v_fmac_f32_e32 v41, v31, v31
	v_fmac_f32_e32 v41, v42, v42
	v_fmac_f32_e32 v41, v43, v43
	s_waitcnt lgkmcnt(0)
	v_sub_f32_e32 v35, v35, v38
	v_fmac_f32_e32 v41, v35, v35
	v_sub_f32_e32 v17, v34, v39
	global_load_dword v38, v[2:3], off
	global_load_dword v34, v[2:3], off offset:128
	global_load_dword v39, v[2:3], off offset:384
	v_fmac_f32_e32 v41, v17, v17
	v_sub_f32_e32 v30, v30, v36
	v_fmac_f32_e32 v41, v30, v30
	v_sub_f32_e32 v29, v29, v37
	v_fmac_f32_e32 v41, v29, v29
	ds_bpermute_b32 v37, v188, v41
	global_load_dword v36, v[2:3], off offset:256
	s_waitcnt lgkmcnt(0)
	v_add_f32_e32 v37, v41, v37
	ds_bpermute_b32 v41, v187, v37
	s_waitcnt lgkmcnt(0)
	v_add_f32_e32 v37, v37, v41
	ds_bpermute_b32 v41, v186, v37
	s_waitcnt lgkmcnt(0)
	v_add_f32_e32 v37, v37, v41
	ds_bpermute_b32 v41, v185, v37
	s_waitcnt lgkmcnt(0)
	v_add_f32_e32 v37, v37, v41
	global_load_dword v41, v[2:3], off offset:896
	ds_bpermute_b32 v47, v184, v37
	s_waitcnt lgkmcnt(0)
	v_add_f32_e32 v37, v37, v47
	v_fmamk_f32 v37, v37, 0x3b800000, v190
	v_mul_f32_e32 v47, 0x4f800000, v37
	v_cmp_gt_f32_e32 vcc, s56, v37
	s_nop 1
	v_cndmask_b32_e32 v37, v37, v47, vcc
	v_sqrt_f32_e32 v47, v37
	s_nop 0
	v_add_u32_e32 v48, -1, v47
	v_fma_f32 v49, -v48, v47, v37
	v_cmp_ge_f32_e64 s[0:1], 0, v49
	v_add_u32_e32 v49, 1, v47
	s_nop 0
	v_cndmask_b32_e64 v48, v47, v48, s[0:1]
	v_fma_f32 v47, -v49, v47, v37
	v_cmp_lt_f32_e64 s[0:1], 0, v47
	s_nop 1
	v_cndmask_b32_e64 v47, v48, v49, s[0:1]
	v_mul_f32_e32 v48, 0x37800000, v47
	v_cndmask_b32_e32 v47, v47, v48, vcc
	v_cmp_class_f32_e32 vcc, v37, v189
	s_nop 1
	v_cndmask_b32_e32 v37, v47, v37, vcc
	v_div_scale_f32 v47, s[0:1], v37, v37, s87
	v_rcp_f32_e32 v48, v47
	s_nop 0
	v_fma_f32 v49, -v47, v48, 1.0
	v_fmac_f32_e32 v48, v49, v48
	v_div_scale_f32 v49, vcc, s87, v37, s87
	v_mul_f32_e32 v50, v49, v48
	v_fma_f32 v51, -v47, v50, v49
	v_fmac_f32_e32 v50, v51, v48
	v_fma_f32 v47, -v47, v50, v49
	v_div_fmas_f32 v47, v47, v48, v50
	v_div_fixup_f32 v37, v47, v37, s87
	v_mul_f32_e32 v31, v31, v37
	s_waitcnt vmcnt(0)
; __device__ __forceinline__ bf16_t f2bf(float f) { unsigned u = __float_as_uint(f); u += 0x7FFFu + ((u >> 16) & 1u); return (bf16_t)(u >> 16); }
; __device__ __forceinline__ void df_unit(LAS unsigned char* lds, const bf16_t* qkv, bf16_t* attout, const float* subg, int b_, int h_, int qb_, int wid, int) {
;     ...
;         for (int r = 0; r < 16; ++r) { const int rowc = (r & 3) + 8 * (r >> 2); float ss = 0.f;
; #pragma unroll
;             for (int d = 0; d < 8; ++d) { o[d][r] -= xr[rowc * 256 + d * 32]; ss += o[d][r] * o[d][r]; }
;             ss += __shfl_xor(ss, 1); ss += __shfl_xor(ss, 2); ss += __shfl_xor(ss, 4); ss += __shfl_xor(ss, 8); ss += __shfl_xor(ss, 16);
;             const float rstd = (1.0f - LAMBDA_INIT) / sqrtf(ss * (1.0f / 256.0f) + SUBLN_EPS);
; #pragma unroll
;             for (int d = 0; d < 8; ++d) op[d * 32] = f2bf(o[d][r] * rstd * subg[d * 32 + r32]);
;             op += ((r & 3) == 3 ? 5 : 1) * DM; asm volatile("" : "+v"(op) :: "memory"); } }
	v_mul_f32_e32 v31, v38, v31
	v_bfe_u32 v38, v31, 16, 1
	v_add3_u32 v31, v31, v38, s88
	global_store_short_d16_hi v[32:33], v31, off
	v_mul_f32_e32 v31, v40, v37
	v_mul_f32_e32 v31, v34, v31
	v_bfe_u32 v34, v31, 16, 1
	v_add3_u32 v31, v31, v34, s88
	global_store_short_d16_hi v[32:33], v31, off offset:64
	v_mul_f32_e32 v31, v42, v37
	v_mul_f32_e32 v31, v36, v31
	v_bfe_u32 v34, v31, 16, 1
	v_add3_u32 v31, v31, v34, s88
	global_store_short_d16_hi v[32:33], v31, off offset:128
	v_mul_f32_e32 v31, v43, v37
	v_mul_f32_e32 v31, v39, v31
	v_bfe_u32 v34, v31, 16, 1
	v_add3_u32 v31, v31, v34, s88
	global_store_short_d16_hi v[32:33], v31, off offset:192
	v_mul_f32_e32 v31, v35, v37
	v_mul_f32_e32 v31, v44, v31
	v_bfe_u32 v34, v31, 16, 1
	v_mul_f32_e32 v17, v17, v37
	v_add3_u32 v31, v31, v34, s88
	v_mul_f32_e32 v17, v17, v45
	global_store_short_d16_hi v[32:33], v31, off offset:256
	v_bfe_u32 v31, v17, 16, 1
	v_add3_u32 v17, v17, v31, s88
	global_store_short_d16_hi v[32:33], v17, off offset:320
	v_mul_f32_e32 v17, v30, v37
	v_mul_f32_e32 v17, v17, v46
	v_bfe_u32 v30, v17, 16, 1
	v_add3_u32 v17, v17, v30, s88
	global_store_short_d16_hi v[32:33], v17, off offset:384
	v_mul_f32_e32 v17, v29, v37
	v_mul_f32_e32 v17, v17, v41
	v_bfe_u32 v29, v17, 16, 1
	v_add3_u32 v17, v17, v29, s88
	global_store_short_d16_hi v[32:33], v17, off offset:448
	v_lshl_add_u64 v[30:31], v[32:33], 0, s[20:21]
	v_add_u32_e32 v17, 0x6400, v13
	ds_read2_b32 v[32:33], v17 offset1:32
	global_load_dword v36, v[2:3], off offset:512
	global_load_dword v37, v[2:3], off offset:640
	global_load_dword v38, v[2:3], off offset:768
	s_waitcnt lgkmcnt(0)
	v_sub_f32_e32 v34, v28, v32
	ds_read2_b32 v[28:29], v17 offset0:64 offset1:96
	v_sub_f32_e32 v27, v27, v33
	ds_read2_b32 v[32:33], v17 offset0:128 offset1:160
	v_mul_f32_e32 v35, v27, v27
	v_fmac_f32_e32 v35, v34, v34
	s_waitcnt lgkmcnt(0)
	v_sub_f32_e32 v26, v26, v28
	v_sub_f32_e32 v28, v25, v29
	v_sub_f32_e32 v29, v24, v32
	ds_read2_b32 v[24:25], v17 offset0:192 offset1:224
	v_fmac_f32_e32 v35, v26, v26
	v_fmac_f32_e32 v35, v28, v28
	v_fmac_f32_e32 v35, v29, v29
	v_sub_f32_e32 v17, v23, v33
	v_fmac_f32_e32 v35, v17, v17
	s_waitcnt lgkmcnt(0)
	v_sub_f32_e32 v22, v22, v24
	v_fmac_f32_e32 v35, v22, v22
	v_sub_f32_e32 v21, v21, v25
	v_fmac_f32_e32 v35, v21, v21
	ds_bpermute_b32 v25, v188, v35
	global_load_dword v32, v[2:3], off
	global_load_dword v23, v[2:3], off offset:128
	global_load_dword v24, v[2:3], off offset:256
	global_load_dword v33, v[2:3], off offset:384
	s_waitcnt lgkmcnt(0)
	v_add_f32_e32 v25, v35, v25
	ds_bpermute_b32 v35, v187, v25
	s_waitcnt lgkmcnt(0)
	v_add_f32_e32 v25, v25, v35
	ds_bpermute_b32 v35, v186, v25
	s_waitcnt lgkmcnt(0)
	v_add_f32_e32 v25, v25, v35
	ds_bpermute_b32 v35, v185, v25
	s_waitcnt lgkmcnt(0)
	v_add_f32_e32 v25, v25, v35
	global_load_dword v35, v[2:3], off offset:896
	ds_bpermute_b32 v39, v184, v25
	s_waitcnt lgkmcnt(0)
	v_add_f32_e32 v25, v25, v39
	v_fmamk_f32 v25, v25, 0x3b800000, v190
	v_mul_f32_e32 v39, 0x4f800000, v25
	v_cmp_gt_f32_e32 vcc, s56, v25
	s_nop 1
	v_cndmask_b32_e32 v25, v25, v39, vcc
	v_sqrt_f32_e32 v39, v25
	s_nop 0
	v_add_u32_e32 v40, -1, v39
	v_fma_f32 v41, -v40, v39, v25
	v_cmp_ge_f32_e64 s[0:1], 0, v41
	v_add_u32_e32 v41, 1, v39
	s_nop 0
	v_cndmask_b32_e64 v40, v39, v40, s[0:1]
	v_fma_f32 v39, -v41, v39, v25
	v_cmp_lt_f32_e64 s[0:1], 0, v39
	s_nop 1
	v_cndmask_b32_e64 v39, v40, v41, s[0:1]
	v_mul_f32_e32 v40, 0x37800000, v39
	v_cndmask_b32_e32 v39, v39, v40, vcc
	v_cmp_class_f32_e32 vcc, v25, v189
	s_nop 1
	v_cndmask_b32_e32 v25, v39, v25, vcc
	v_div_scale_f32 v39, s[0:1], v25, v25, s87
	v_rcp_f32_e32 v40, v39
	s_nop 0
	v_fma_f32 v41, -v39, v40, 1.0
	v_fmac_f32_e32 v40, v41, v40
	v_div_scale_f32 v41, vcc, s87, v25, s87
	v_mul_f32_e32 v42, v41, v40
	v_fma_f32 v43, -v39, v42, v41
	v_fmac_f32_e32 v42, v43, v40
	v_fma_f32 v39, -v39, v42, v41
	v_div_fmas_f32 v39, v39, v40, v42
	v_div_fixup_f32 v25, v39, v25, s87
	v_mul_f32_e32 v27, v27, v25
	v_mul_f32_e32 v17, v17, v25
	s_waitcnt vmcnt(0)
	v_mul_f32_e32 v17, v17, v37
	v_mul_f32_e32 v34, v34, v25
	v_mul_f32_e32 v32, v32, v34
	v_mul_f32_e32 v23, v23, v27
	v_bfe_u32 v27, v23, 16, 1
	v_add3_u32 v23, v23, v27, s88
	global_store_short_d16_hi v[30:31], v23, off offset:64
	v_mul_f32_e32 v23, v26, v25
	v_mul_f32_e32 v23, v24, v23
	v_bfe_u32 v24, v23, 16, 1
	v_add3_u32 v23, v23, v24, s88
	global_store_short_d16_hi v[30:31], v23, off offset:128
	v_mul_f32_e32 v23, v28, v25
	v_mul_f32_e32 v23, v33, v23
	v_bfe_u32 v24, v23, 16, 1
	v_add3_u32 v23, v23, v24, s88
	global_store_short_d16_hi v[30:31], v23, off offset:192
	v_mul_f32_e32 v23, v29, v25
	v_mul_f32_e32 v23, v36, v23
	v_bfe_u32 v24, v23, 16, 1
	v_add3_u32 v23, v23, v24, s88
	global_store_short_d16_hi v[30:31], v23, off offset:256
	v_bfe_u32 v23, v17, 16, 1
	v_add3_u32 v17, v17, v23, s88
	global_store_short_d16_hi v[30:31], v17, off offset:320
	v_mul_f32_e32 v17, v22, v25
	v_mul_f32_e32 v17, v17, v38
	v_bfe_u32 v22, v17, 16, 1
	v_add3_u32 v17, v17, v22, s88
	global_store_short_d16_hi v[30:31], v17, off offset:384
	v_mul_f32_e32 v17, v21, v25
	v_mul_f32_e32 v17, v17, v35
	v_bfe_u32 v34, v32, 16, 1
	v_bfe_u32 v21, v17, 16, 1
	v_add3_u32 v32, v32, v34, s88
	v_add3_u32 v17, v17, v21, s88
	global_store_short_d16_hi v[30:31], v32, off
	global_store_short_d16_hi v[30:31], v17, off offset:448
	v_lshl_add_u64 v[22:23], v[30:31], 0, s[20:21]
	v_add_u32_e32 v17, 0x6800, v13
	ds_read2_b32 v[24:25], v17 offset1:32
	global_load_dword v28, v[2:3], off offset:512
	global_load_dword v29, v[2:3], off offset:640
	global_load_dword v30, v[2:3], off offset:768
	s_waitcnt lgkmcnt(0)
; __device__ __forceinline__ bf16_t f2bf(float f) { unsigned u = __float_as_uint(f); u += 0x7FFFu + ((u >> 16) & 1u); return (bf16_t)(u >> 16); }
; __device__ __forceinline__ void df_unit(LAS unsigned char* lds, const bf16_t* qkv, bf16_t* attout, const float* subg, int b_, int h_, int qb_, int wid, int) {
;     ...
;         for (int r = 0; r < 16; ++r) { const int rowc = (r & 3) + 8 * (r >> 2); float ss = 0.f;
; #pragma unroll
;             for (int d = 0; d < 8; ++d) { o[d][r] -= xr[rowc * 256 + d * 32]; ss += o[d][r] * o[d][r]; }
;             ss += __shfl_xor(ss, 1); ss += __shfl_xor(ss, 2); ss += __shfl_xor(ss, 4); ss += __shfl_xor(ss, 8); ss += __shfl_xor(ss, 16);
;             const float rstd = (1.0f - LAMBDA_INIT) / sqrtf(ss * (1.0f / 256.0f) + SUBLN_EPS);
; #pragma unroll
;             for (int d = 0; d < 8; ++d) op[d * 32] = f2bf(o[d][r] * rstd * subg[d * 32 + r32]);
;             op += ((r & 3) == 3 ? 5 : 1) * DM; asm volatile("" : "+v"(op) :: "memory"); } }
	v_sub_f32_e32 v26, v20, v24
	ds_read2_b32 v[20:21], v17 offset0:64 offset1:96
	v_sub_f32_e32 v19, v19, v25
	ds_read2_b32 v[24:25], v17 offset0:128 offset1:160
	v_mul_f32_e32 v27, v19, v19
	v_fmac_f32_e32 v27, v26, v26
	s_waitcnt lgkmcnt(0)
	v_sub_f32_e32 v18, v18, v20
	v_sub_f32_e32 v20, v16, v21
	ds_read2_b32 v[16:17], v17 offset0:192 offset1:224
	v_fmac_f32_e32 v27, v18, v18
	v_fmac_f32_e32 v27, v20, v20
	v_sub_f32_e32 v15, v15, v24
	v_fmac_f32_e32 v27, v15, v15
	v_sub_f32_e32 v14, v14, v25
	v_fmac_f32_e32 v27, v14, v14
	s_waitcnt lgkmcnt(0)
	v_sub_f32_e32 v11, v11, v16
	v_fmac_f32_e32 v27, v11, v11
	v_sub_f32_e32 v12, v12, v17
	v_fmac_f32_e32 v27, v12, v12
	ds_bpermute_b32 v17, v188, v27
	global_load_dword v21, v[2:3], off
	global_load_dword v24, v[2:3], off offset:128
	global_load_dword v16, v[2:3], off offset:256
	global_load_dword v25, v[2:3], off offset:384
	s_waitcnt lgkmcnt(0)
	v_add_f32_e32 v17, v27, v17
	ds_bpermute_b32 v27, v187, v17
	s_waitcnt lgkmcnt(0)
	v_add_f32_e32 v17, v17, v27
	ds_bpermute_b32 v27, v186, v17
	s_waitcnt lgkmcnt(0)
	v_add_f32_e32 v17, v17, v27
	ds_bpermute_b32 v27, v185, v17
	s_waitcnt lgkmcnt(0)
	v_add_f32_e32 v17, v17, v27
	global_load_dword v27, v[2:3], off offset:896
	ds_bpermute_b32 v31, v184, v17
	s_waitcnt lgkmcnt(0)
	v_add_f32_e32 v17, v17, v31
	v_fmamk_f32 v17, v17, 0x3b800000, v190
	v_mul_f32_e32 v31, 0x4f800000, v17
	v_cmp_gt_f32_e32 vcc, s56, v17
	s_nop 1
	v_cndmask_b32_e32 v17, v17, v31, vcc
	v_sqrt_f32_e32 v31, v17
	s_nop 0
	v_add_u32_e32 v32, -1, v31
	v_fma_f32 v33, -v32, v31, v17
	v_cmp_ge_f32_e64 s[0:1], 0, v33
	v_add_u32_e32 v33, 1, v31
	s_nop 0
	v_cndmask_b32_e64 v32, v31, v32, s[0:1]
	v_fma_f32 v31, -v33, v31, v17
	v_cmp_lt_f32_e64 s[0:1], 0, v31
	s_nop 1
	v_cndmask_b32_e64 v31, v32, v33, s[0:1]
	v_mul_f32_e32 v32, 0x37800000, v31
	v_cndmask_b32_e32 v31, v31, v32, vcc
	v_cmp_class_f32_e32 vcc, v17, v189
	s_nop 1
	v_cndmask_b32_e32 v17, v31, v17, vcc
	v_div_scale_f32 v31, s[0:1], v17, v17, s87
	v_rcp_f32_e32 v32, v31
	s_nop 0
	v_fma_f32 v33, -v31, v32, 1.0
	v_fmac_f32_e32 v32, v33, v32
	v_div_scale_f32 v33, vcc, s87, v17, s87
	v_mul_f32_e32 v34, v33, v32
	v_fma_f32 v35, -v31, v34, v33
	v_fmac_f32_e32 v34, v35, v32
	v_fma_f32 v31, -v31, v34, v33
	v_div_fmas_f32 v31, v31, v32, v34
	v_div_fixup_f32 v17, v31, v17, s87
	v_mul_f32_e32 v18, v18, v17
	v_mul_f32_e32 v15, v15, v17
	s_waitcnt vmcnt(0)
	v_mul_f32_e32 v15, v28, v15
	v_mul_f32_e32 v14, v14, v17
	v_mul_f32_e32 v14, v14, v29
	v_mul_f32_e32 v11, v11, v17
	v_mul_f32_e32 v11, v11, v30
	v_mul_f32_e32 v26, v26, v17
	v_mul_f32_e32 v21, v21, v26
	v_mul_f32_e32 v16, v16, v18
	v_bfe_u32 v18, v16, 16, 1
	v_add3_u32 v16, v16, v18, s88
	global_store_short_d16_hi v[22:23], v16, off offset:128
	v_mul_f32_e32 v16, v20, v17
	v_mul_f32_e32 v16, v25, v16
	v_bfe_u32 v18, v16, 16, 1
	v_add3_u32 v16, v16, v18, s88
	global_store_short_d16_hi v[22:23], v16, off offset:192
	v_bfe_u32 v16, v15, 16, 1
	v_add3_u32 v15, v15, v16, s88
	global_store_short_d16_hi v[22:23], v15, off offset:256
	v_bfe_u32 v15, v14, 16, 1
	v_add3_u32 v14, v14, v15, s88
	global_store_short_d16_hi v[22:23], v14, off offset:320
	v_bfe_u32 v14, v11, 16, 1
	v_add3_u32 v11, v11, v14, s88
	v_bfe_u32 v26, v21, 16, 1
	v_mul_f32_e32 v19, v19, v17
	global_store_short_d16_hi v[22:23], v11, off offset:384
	v_mul_f32_e32 v11, v12, v17
	v_add3_u32 v21, v21, v26, s88
	v_mul_f32_e32 v19, v24, v19
	v_mul_f32_e32 v11, v11, v27
	global_store_short_d16_hi v[22:23], v21, off
	v_bfe_u32 v21, v19, 16, 1
	v_bfe_u32 v12, v11, 16, 1
	v_add3_u32 v19, v19, v21, s88
	v_add3_u32 v11, v11, v12, s88
	global_store_short_d16_hi v[22:23], v19, off offset:64
	global_store_short_d16_hi v[22:23], v11, off offset:448
	v_lshl_add_u64 v[14:15], v[22:23], 0, s[20:21]
	v_add_u32_e32 v16, 0x6c00, v13
	ds_read2_b32 v[12:13], v16 offset1:32
	global_load_dword v19, v[2:3], off offset:512
	global_load_dword v20, v[2:3], off offset:640
	global_load_dword v21, v[2:3], off offset:768
	s_waitcnt lgkmcnt(0)
; #define LAS __attribute__((address_space(3)))
; __device__ __forceinline__ bf16_t f2bf(float f) { unsigned u = __float_as_uint(f); u += 0x7FFFu + ((u >> 16) & 1u); return (bf16_t)(u >> 16); }
; __device__ __forceinline__ void df_unit(LAS unsigned char* lds, const bf16_t* qkv, bf16_t* attout, const float* subg, int b_, int h_, int qb_, int wid, int) {
;     ...
;     if (jsel == 0) {
;         bf16_t* op = attout + (size_t)(b * SEQ + q0 + 4 * hi) * DM + 1024 + h * 256 + r32; const LAS float* xr = xb + (4 * hi) * 256 + r32;
; #pragma unroll
;         for (int r = 0; r < 16; ++r) { const int rowc = (r & 3) + 8 * (r >> 2); float ss = 0.f;
; #pragma unroll
;             for (int d = 0; d < 8; ++d) { o[d][r] -= xr[rowc * 256 + d * 32]; ss += o[d][r] * o[d][r]; }
;             ss += __shfl_xor(ss, 1); ss += __shfl_xor(ss, 2); ss += __shfl_xor(ss, 4); ss += __shfl_xor(ss, 8); ss += __shfl_xor(ss, 16);
;             const float rstd = (1.0f - LAMBDA_INIT) / sqrtf(ss * (1.0f / 256.0f) + SUBLN_EPS);
; #pragma unroll
;             for (int d = 0; d < 8; ++d) op[d * 32] = f2bf(o[d][r] * rstd * subg[d * 32 + r32]);
;             op += ((r & 3) == 3 ? 5 : 1) * DM; asm volatile("" : "+v"(op) :: "memory"); } }
	v_sub_f32_e32 v17, v10, v12
	ds_read2_b32 v[10:11], v16 offset0:64 offset1:96
	v_sub_f32_e32 v9, v9, v13
	ds_read2_b32 v[12:13], v16 offset0:128 offset1:160
	v_mul_f32_e32 v18, v9, v9
	v_fmac_f32_e32 v18, v17, v17
	s_waitcnt lgkmcnt(0)
	v_sub_f32_e32 v8, v8, v10
	v_sub_f32_e32 v10, v7, v11
	v_sub_f32_e32 v11, v6, v12
	global_load_dword v12, v[2:3], off
	ds_read2_b32 v[6:7], v16 offset0:192 offset1:224
	v_sub_f32_e32 v5, v5, v13
	global_load_dword v13, v[2:3], off offset:128
	global_load_dword v16, v[2:3], off offset:384
	v_fmac_f32_e32 v18, v8, v8
	s_waitcnt lgkmcnt(0)
	v_sub_f32_e32 v4, v4, v6
	global_load_dword v6, v[2:3], off offset:256
	v_fmac_f32_e32 v18, v10, v10
	v_fmac_f32_e32 v18, v11, v11
	v_fmac_f32_e32 v18, v5, v5
	v_fmac_f32_e32 v18, v4, v4
	v_sub_f32_e32 v0, v0, v7
	v_fmac_f32_e32 v18, v0, v0
	ds_bpermute_b32 v7, v188, v18
	global_load_dword v2, v[2:3], off offset:896
	s_waitcnt lgkmcnt(0)
	v_add_f32_e32 v7, v18, v7
	ds_bpermute_b32 v18, v187, v7
	s_waitcnt lgkmcnt(0)
	v_add_f32_e32 v7, v7, v18
	ds_bpermute_b32 v18, v186, v7
	s_waitcnt lgkmcnt(0)
	v_add_f32_e32 v7, v7, v18
	ds_bpermute_b32 v18, v185, v7
	s_waitcnt lgkmcnt(0)
	v_add_f32_e32 v7, v7, v18
	ds_bpermute_b32 v3, v184, v7
	s_waitcnt lgkmcnt(0)
	v_add_f32_e32 v3, v7, v3
	v_fmamk_f32 v3, v3, 0x3b800000, v190
	v_mul_f32_e32 v7, 0x4f800000, v3
	v_cmp_gt_f32_e32 vcc, s56, v3
	s_nop 1
	v_cndmask_b32_e32 v3, v3, v7, vcc
	v_sqrt_f32_e32 v7, v3
	s_nop 0
	v_add_u32_e32 v18, -1, v7
	v_fma_f32 v22, -v18, v7, v3
	v_cmp_ge_f32_e64 s[0:1], 0, v22
	v_add_u32_e32 v22, 1, v7
	s_nop 0
	v_cndmask_b32_e64 v18, v7, v18, s[0:1]
	v_fma_f32 v7, -v22, v7, v3
	v_cmp_lt_f32_e64 s[0:1], 0, v7
	s_nop 1
	v_cndmask_b32_e64 v7, v18, v22, s[0:1]
	v_mul_f32_e32 v18, 0x37800000, v7
	v_cndmask_b32_e32 v7, v7, v18, vcc
	v_cmp_class_f32_e32 vcc, v3, v189
	s_nop 1
	v_cndmask_b32_e32 v3, v7, v3, vcc
	v_div_scale_f32 v7, s[0:1], v3, v3, s87
	v_rcp_f32_e32 v18, v7
	s_nop 0
	v_fma_f32 v22, -v7, v18, 1.0
	v_fmac_f32_e32 v18, v22, v18
	v_div_scale_f32 v22, vcc, s87, v3, s87
	v_mul_f32_e32 v23, v22, v18
	v_fma_f32 v24, -v7, v23, v22
	v_fmac_f32_e32 v23, v24, v18
	v_fma_f32 v7, -v7, v23, v22
	v_div_fmas_f32 v7, v7, v18, v23
	v_div_fixup_f32 v3, v7, v3, s87
	v_mul_f32_e32 v7, v17, v3
	s_waitcnt vmcnt(0)
	v_mul_f32_e32 v7, v12, v7
	v_bfe_u32 v12, v7, 16, 1
	v_add3_u32 v7, v7, v12, s88
	global_store_short_d16_hi v[14:15], v7, off
	v_mul_f32_e32 v7, v9, v3
	v_mul_f32_e32 v7, v13, v7
	v_bfe_u32 v9, v7, 16, 1
	v_add3_u32 v7, v7, v9, s88
	global_store_short_d16_hi v[14:15], v7, off offset:64
	v_mul_f32_e32 v7, v8, v3
	v_mul_f32_e32 v6, v6, v7
	v_bfe_u32 v7, v6, 16, 1
	v_add3_u32 v6, v6, v7, s88
	global_store_short_d16_hi v[14:15], v6, off offset:128
	v_mul_f32_e32 v6, v10, v3
	v_mul_f32_e32 v6, v16, v6
	v_bfe_u32 v7, v6, 16, 1
	v_add3_u32 v6, v6, v7, s88
	global_store_short_d16_hi v[14:15], v6, off offset:192
	v_mul_f32_e32 v6, v11, v3
	v_mul_f32_e32 v6, v19, v6
	v_bfe_u32 v7, v6, 16, 1
	v_mul_f32_e32 v5, v5, v3
	v_add3_u32 v6, v6, v7, s88
	v_mul_f32_e32 v5, v5, v20
	global_store_short_d16_hi v[14:15], v6, off offset:256
	v_bfe_u32 v6, v5, 16, 1
	v_mul_f32_e32 v4, v4, v3
	v_mul_f32_e32 v0, v0, v3
	v_add3_u32 v5, v5, v6, s88
	v_mul_f32_e32 v4, v4, v21
	v_mul_f32_e32 v0, v0, v2
	global_store_short_d16_hi v[14:15], v5, off offset:320
	v_bfe_u32 v5, v4, 16, 1
	v_bfe_u32 v2, v0, 16, 1
	v_add3_u32 v4, v4, v5, s88
	v_add3_u32 v0, v0, v2, s88
	global_store_short_d16_hi v[14:15], v4, off offset:384
	global_store_short_d16_hi v[14:15], v0, off offset:448
	v_lshl_add_u64 v[2:3], v[14:15], 0, s[22:23]
	s_branch .LBB0_260

; __device__ __forceinline__ bf16_t f2bf(float f) { unsigned u = __float_as_uint(f); u += 0x7FFFu + ((u >> 16) & 1u); return (bf16_t)(u >> 16); }
; __device__ __forceinline__ void sb_unit(LAS unsigned char* lds, const bf16_t* qkv, bf16_t* attout, int b, int h, int qb, int wid, int) {
;     ...
;     asm volatile("" : "+v"(hi), "+v"(r32));
;     bf16_t* op = attout + (size_t)(b * SEQ + q0 + 4 * hi) * DM + h * 128 + r32;
; #pragma unroll
;     for (int r = 0; r < 16; ++r) {
; #pragma unroll
;         for (int d0 = 0; d0 < 4; ++d0) op[d0 * 32] = f2bf(o[d0][r]);
;         op += ((r & 3) == 3 ? 5 : 1) * DM; asm volatile("" : "+v"(op) :: "memory"); }
.LBB0_304:
	s_lshl_b32 s1, s33, 12
	s_add_i32 s43, s43, s1
	s_lshl_b32 s0, s42, 7
	v_lshl_add_u32 v2, v193, 2, s43
	v_ashrrev_i32_e32 v3, 31, v2
	v_lshlrev_b64 v[2:3], 12, v[2:3]
	v_lshl_add_u64 v[2:3], s[44:45], 0, v[2:3]
	s_lshl_b32 s46, s0, 1
	v_lshl_add_u64 v[2:3], v[2:3], 0, s[46:47]
	v_ashrrev_i32_e32 v193, 31, v192
	v_bfe_u32 v0, v112, 16, 1
	v_lshl_add_u64 v[2:3], v[192:193], 1, v[2:3]
	v_add3_u32 v0, v112, v0, s83
	global_store_short_d16_hi v[2:3], v0, off
	v_bfe_u32 v0, v80, 16, 1
	v_add3_u32 v0, v80, v0, s83
	global_store_short_d16_hi v[2:3], v0, off offset:64
	v_bfe_u32 v0, v96, 16, 1
	v_add3_u32 v0, v96, v0, s83
	global_store_short_d16_hi v[2:3], v0, off offset:128
	v_bfe_u32 v0, v128, 16, 1
	v_add3_u32 v0, v128, v0, s83
	global_store_short_d16_hi v[2:3], v0, off offset:192
	v_bfe_u32 v0, v113, 16, 1
	v_lshl_add_u64 v[2:3], v[2:3], 0, s[48:49]
	v_add3_u32 v0, v113, v0, s83
	global_store_short_d16_hi v[2:3], v0, off
	v_bfe_u32 v0, v81, 16, 1
	v_add3_u32 v0, v81, v0, s83
	global_store_short_d16_hi v[2:3], v0, off offset:64
	v_bfe_u32 v0, v97, 16, 1
	v_add3_u32 v0, v97, v0, s83
	global_store_short_d16_hi v[2:3], v0, off offset:128
	v_bfe_u32 v0, v129, 16, 1
	v_add3_u32 v0, v129, v0, s83
	global_store_short_d16_hi v[2:3], v0, off offset:192
	v_bfe_u32 v0, v114, 16, 1
	v_lshl_add_u64 v[2:3], v[2:3], 0, s[48:49]
	v_add3_u32 v0, v114, v0, s83
	global_store_short_d16_hi v[2:3], v0, off
	v_bfe_u32 v0, v82, 16, 1
	v_add3_u32 v0, v82, v0, s83
	global_store_short_d16_hi v[2:3], v0, off offset:64
	v_bfe_u32 v0, v98, 16, 1
	v_add3_u32 v0, v98, v0, s83
	global_store_short_d16_hi v[2:3], v0, off offset:128
	v_bfe_u32 v0, v130, 16, 1
	v_add3_u32 v0, v130, v0, s83
	global_store_short_d16_hi v[2:3], v0, off offset:192
	v_bfe_u32 v0, v115, 16, 1
	v_lshl_add_u64 v[2:3], v[2:3], 0, s[48:49]
	v_add3_u32 v0, v115, v0, s83
	global_store_short_d16_hi v[2:3], v0, off
	v_bfe_u32 v0, v83, 16, 1
	v_add3_u32 v0, v83, v0, s83
	global_store_short_d16_hi v[2:3], v0, off offset:64
	v_bfe_u32 v0, v99, 16, 1
	v_add3_u32 v0, v99, v0, s83
	global_store_short_d16_hi v[2:3], v0, off offset:128
	v_bfe_u32 v0, v131, 16, 1
	v_add3_u32 v0, v131, v0, s83
	global_store_short_d16_hi v[2:3], v0, off offset:192
	v_bfe_u32 v0, v116, 16, 1
	v_lshl_add_u64 v[2:3], v[2:3], 0, s[56:57]
	v_add3_u32 v0, v116, v0, s83
	global_store_short_d16_hi v[2:3], v0, off
	v_bfe_u32 v0, v84, 16, 1
	v_add3_u32 v0, v84, v0, s83
	global_store_short_d16_hi v[2:3], v0, off offset:64
	v_bfe_u32 v0, v100, 16, 1
	v_add3_u32 v0, v100, v0, s83
	global_store_short_d16_hi v[2:3], v0, off offset:128
	v_bfe_u32 v0, v132, 16, 1
	v_add3_u32 v0, v132, v0, s83
	global_store_short_d16_hi v[2:3], v0, off offset:192
	v_bfe_u32 v0, v117, 16, 1
	v_lshl_add_u64 v[2:3], v[2:3], 0, s[48:49]
	v_add3_u32 v0, v117, v0, s83
	global_store_short_d16_hi v[2:3], v0, off
	v_bfe_u32 v0, v85, 16, 1
	v_add3_u32 v0, v85, v0, s83
	global_store_short_d16_hi v[2:3], v0, off offset:64
	v_bfe_u32 v0, v101, 16, 1
	v_add3_u32 v0, v101, v0, s83
	global_store_short_d16_hi v[2:3], v0, off offset:128
	v_bfe_u32 v0, v133, 16, 1
	v_add3_u32 v0, v133, v0, s83
	global_store_short_d16_hi v[2:3], v0, off offset:192
	v_bfe_u32 v0, v118, 16, 1
	v_lshl_add_u64 v[2:3], v[2:3], 0, s[48:49]
	v_add3_u32 v0, v118, v0, s83
	global_store_short_d16_hi v[2:3], v0, off
	v_bfe_u32 v0, v86, 16, 1
	v_add3_u32 v0, v86, v0, s83
	global_store_short_d16_hi v[2:3], v0, off offset:64
	v_bfe_u32 v0, v102, 16, 1
	v_add3_u32 v0, v102, v0, s83
	global_store_short_d16_hi v[2:3], v0, off offset:128
	v_bfe_u32 v0, v134, 16, 1
	v_add3_u32 v0, v134, v0, s83
	global_store_short_d16_hi v[2:3], v0, off offset:192
	v_bfe_u32 v0, v119, 16, 1
	v_lshl_add_u64 v[2:3], v[2:3], 0, s[48:49]
	v_add3_u32 v0, v119, v0, s83
	global_store_short_d16_hi v[2:3], v0, off
	v_bfe_u32 v0, v87, 16, 1
	v_add3_u32 v0, v87, v0, s83
	global_store_short_d16_hi v[2:3], v0, off offset:64
	v_bfe_u32 v0, v103, 16, 1
	v_add3_u32 v0, v103, v0, s83
	global_store_short_d16_hi v[2:3], v0, off offset:128
; __device__ __forceinline__ bf16_t f2bf(float f) { unsigned u = __float_as_uint(f); u += 0x7FFFu + ((u >> 16) & 1u); return (bf16_t)(u >> 16); }
; __device__ __forceinline__ void sb_unit(LAS unsigned char* lds, const bf16_t* qkv, bf16_t* attout, int b, int h, int qb, int wid, int) {
;     ...
;     asm volatile("" : "+v"(hi), "+v"(r32));
;     bf16_t* op = attout + (size_t)(b * SEQ + q0 + 4 * hi) * DM + h * 128 + r32;
; #pragma unroll
;     for (int r = 0; r < 16; ++r) {
; #pragma unroll
;         for (int d0 = 0; d0 < 4; ++d0) op[d0 * 32] = f2bf(o[d0][r]);
;         op += ((r & 3) == 3 ? 5 : 1) * DM; asm volatile("" : "+v"(op) :: "memory"); }
; __device__ void phase_attn(const Args& A, LAS unsigned char* lds, int wid_in) {
;     ...
;     if (!g1) for (int u = i0; u < 512; u += st) { const int qb = u >> 5, b = (u & 7) >> 1, h = ((u & 1) << 2) | ((u >> 3) & 3); sb_unit(lds, qkv, attout, b, h, qb, wid, lane); }
	v_bfe_u32 v0, v135, 16, 1
	v_add3_u32 v0, v135, v0, s83
	global_store_short_d16_hi v[2:3], v0, off offset:192
	v_bfe_u32 v0, v120, 16, 1
	v_lshl_add_u64 v[2:3], v[2:3], 0, s[56:57]
	v_add3_u32 v0, v120, v0, s83
	global_store_short_d16_hi v[2:3], v0, off
	v_bfe_u32 v0, v88, 16, 1
	v_add3_u32 v0, v88, v0, s83
	global_store_short_d16_hi v[2:3], v0, off offset:64
	v_bfe_u32 v0, v104, 16, 1
	v_add3_u32 v0, v104, v0, s83
	global_store_short_d16_hi v[2:3], v0, off offset:128
	v_bfe_u32 v0, v136, 16, 1
	v_add3_u32 v0, v136, v0, s83
	global_store_short_d16_hi v[2:3], v0, off offset:192
	v_bfe_u32 v0, v121, 16, 1
	v_lshl_add_u64 v[2:3], v[2:3], 0, s[48:49]
	v_add3_u32 v0, v121, v0, s83
	global_store_short_d16_hi v[2:3], v0, off
	v_bfe_u32 v0, v89, 16, 1
	v_add3_u32 v0, v89, v0, s83
	global_store_short_d16_hi v[2:3], v0, off offset:64
	v_bfe_u32 v0, v105, 16, 1
	v_add3_u32 v0, v105, v0, s83
	global_store_short_d16_hi v[2:3], v0, off offset:128
	v_bfe_u32 v0, v137, 16, 1
	v_add3_u32 v0, v137, v0, s83
	global_store_short_d16_hi v[2:3], v0, off offset:192
	v_bfe_u32 v0, v122, 16, 1
	v_lshl_add_u64 v[2:3], v[2:3], 0, s[48:49]
	v_add3_u32 v0, v122, v0, s83
	global_store_short_d16_hi v[2:3], v0, off
	v_bfe_u32 v0, v90, 16, 1
	v_add3_u32 v0, v90, v0, s83
	global_store_short_d16_hi v[2:3], v0, off offset:64
	v_bfe_u32 v0, v106, 16, 1
	v_add3_u32 v0, v106, v0, s83
	global_store_short_d16_hi v[2:3], v0, off offset:128
	v_bfe_u32 v0, v138, 16, 1
	v_add3_u32 v0, v138, v0, s83
	global_store_short_d16_hi v[2:3], v0, off offset:192
	v_bfe_u32 v0, v123, 16, 1
	v_lshl_add_u64 v[2:3], v[2:3], 0, s[48:49]
	v_add3_u32 v0, v123, v0, s83
	global_store_short_d16_hi v[2:3], v0, off
	v_bfe_u32 v0, v91, 16, 1
	v_add3_u32 v0, v91, v0, s83
	global_store_short_d16_hi v[2:3], v0, off offset:64
	v_bfe_u32 v0, v107, 16, 1
	v_add3_u32 v0, v107, v0, s83
	global_store_short_d16_hi v[2:3], v0, off offset:128
	v_bfe_u32 v0, v139, 16, 1
	v_add3_u32 v0, v139, v0, s83
	global_store_short_d16_hi v[2:3], v0, off offset:192
	v_bfe_u32 v0, v124, 16, 1
	v_lshl_add_u64 v[2:3], v[2:3], 0, s[56:57]
	v_add3_u32 v0, v124, v0, s83
	global_store_short_d16_hi v[2:3], v0, off
	v_bfe_u32 v0, v92, 16, 1
	v_add3_u32 v0, v92, v0, s83
	global_store_short_d16_hi v[2:3], v0, off offset:64
	v_bfe_u32 v0, v108, 16, 1
	v_add3_u32 v0, v108, v0, s83
	global_store_short_d16_hi v[2:3], v0, off offset:128
	v_bfe_u32 v0, v140, 16, 1
	v_add3_u32 v0, v140, v0, s83
	global_store_short_d16_hi v[2:3], v0, off offset:192
	v_bfe_u32 v0, v125, 16, 1
	v_lshl_add_u64 v[2:3], v[2:3], 0, s[48:49]
	v_add3_u32 v0, v125, v0, s83
	global_store_short_d16_hi v[2:3], v0, off
	v_bfe_u32 v0, v93, 16, 1
	v_add3_u32 v0, v93, v0, s83
	global_store_short_d16_hi v[2:3], v0, off offset:64
	v_bfe_u32 v0, v109, 16, 1
	v_add3_u32 v0, v109, v0, s83
	global_store_short_d16_hi v[2:3], v0, off offset:128
	v_bfe_u32 v0, v141, 16, 1
	v_add3_u32 v0, v141, v0, s83
	global_store_short_d16_hi v[2:3], v0, off offset:192
	v_bfe_u32 v0, v126, 16, 1
	v_lshl_add_u64 v[2:3], v[2:3], 0, s[48:49]
	v_add3_u32 v0, v126, v0, s83
	global_store_short_d16_hi v[2:3], v0, off
	v_bfe_u32 v0, v94, 16, 1
	v_add3_u32 v0, v94, v0, s83
	global_store_short_d16_hi v[2:3], v0, off offset:64
	v_bfe_u32 v0, v110, 16, 1
	v_add3_u32 v0, v110, v0, s83
	global_store_short_d16_hi v[2:3], v0, off offset:128
	v_bfe_u32 v0, v142, 16, 1
	v_add3_u32 v0, v142, v0, s83
	global_store_short_d16_hi v[2:3], v0, off offset:192
	v_bfe_u32 v0, v127, 16, 1
	v_lshl_add_u64 v[2:3], v[2:3], 0, s[48:49]
	v_add3_u32 v0, v127, v0, s83
	global_store_short_d16_hi v[2:3], v0, off
	v_bfe_u32 v0, v95, 16, 1
	v_add3_u32 v0, v95, v0, s83
	global_store_short_d16_hi v[2:3], v0, off offset:64
	v_bfe_u32 v0, v111, 16, 1
	v_add3_u32 v0, v111, v0, s83
	global_store_short_d16_hi v[2:3], v0, off offset:128
	v_bfe_u32 v0, v143, 16, 1
	v_add3_u32 v0, v143, v0, s83
	global_store_short_d16_hi v[2:3], v0, off offset:192
	v_lshl_add_u64 v[2:3], v[2:3], 0, s[56:57]
	s_add_i32 s70, s70, s69
	s_cmpk_lt_i32 s70, 0x200
	s_cbranch_scc0 .LBB0_347
